# lora: weight blocks staged global->registers->shared LDS (two buffers, 2-step rolled loop), biases from LDS, and the sample items' 16 carried-state loads issued together (lanes 0-15, moved into place
# speedup vs baseline: 1.0064x; 1.0064x over previous
; #define LAS __attribute__((address_space(3)))
; __device__ __forceinline__ unsigned pk2(float lo, float hi) { f32x2 v = {lo, hi}; bf16x2_t b = __builtin_convertvector(v, bf16x2_t); return __builtin_bit_cast(unsigned, b); }
; __device__ __forceinline__ float sigmoidf_(float x) { return frcp(1.f + fexp2(-1.4426950408889634f * x)); }
;     __device__ __forceinline__ const float* in(int i) const { return (const float*)ptr(i); }
; __device__ __forceinline__ void unpack8(const u32x4 w, float (&f)[8]) { f[0] = bflo(w.x); f[1] = bfhi(w.x); f[2] = bflo(w.y); f[3] = bfhi(w.y); f[4] = bflo(w.z); f[5] = bfhi(w.z); f[6] = bflo(w.w); f[7] = bfhi(w.w); }
; __device__ __forceinline__ void zshift8(const Ctx& p, const bf16_t* ZRW, int row, int c, const float (&mu)[8], float (&o)[8]) {
;     float z[8], pv[8];
;     unpack8(*(const u32x4*)(ZRW + (size_t)row * SHW + c), z);
;     bool first; int bsmp = 0;
;     if (row < MPR) first = (row & (TP - 1)) == 0; else { first = ((row - MPR) & 15) == 0; bsmp = (row - MPR) >> 4; }
;     if (!first) unpack8(*(const u32x4*)(ZRW + (size_t)(row - 1) * SHW + c), pv);
;     else if (row < MPR) {
; #pragma unroll
;         for (int e = 0; e < 8; ++e) pv[e] = 0.f;
;     } else { const float* s0 = p.in(5) + (size_t)bsmp * SHW + c;
; #pragma unroll
;         for (int e = 0; e < 8; ++e) pv[e] = s0[e]; }
; __device__ __forceinline__ void phase_lora(const Ctx& p, LAS unsigned char* lds) {
;     ...
;     for (int it = blockIdx.x + gridDim.x * wave; it < MR / 16; it += gridDim.x * 8) {
;         const int r0 = it * 16;
;         {
;             const int tt = lane >> 2, cq = lane & 3, row = r0 + tt;
; #pragma unroll
;             for (int j = 0; j < 8; ++j) {
;                 const int c = cq * 64 + j * 8;
;                 float m8[8], z[8];
; #pragma unroll
;                 for (int e = 0; e < 8; ++e) m8[e] = mu[c + e];
;                 zshift8(p, ZRW, row, 1536 + c, m8, z);
; #pragma unroll
;                 for (int e = 0; e < 8; ++e) z[e] = cq == 0 ? tanhf(z[e]) : (cq == 1 ? z[e] : sigmoidf_(z[e]));
;                 u32x4 w; w.x = pk2(z[0], z[1]); w.y = pk2(z[2], z[3]); w.z = pk2(z[4], z[5]); w.w = pk2(z[6], z[7]);
;                 *(LAS u32x4*)(X + tt * 264 + c) = w;
.Llora_item:
	s_cmpk_gt_i32 s26, 0x407
	s_cbranch_scc1 .Llora_done
	s_and_b32 s2, s26, 0xff
	s_cmp_eq_u32 s2, 0
	s_cselect_b32 s52, 1, 0
	s_cmpk_gt_i32 s26, 0x3ff
	s_cselect_b32 s53, 1, 0
	s_or_b32 s52, s52, s53
	s_lshl_b32 s2, s26, 4
	v_add_u32_e32 v3, s2, v1
	v_mul_u32_u24_e32 v3, 0xe00, v3
	v_lshl_add_u32 v3, v2, 7, v3
	v_add_u32_e32 v3, 0xc00, v3
	v_subrev_u32_e32 v4, 0xe00, v3
	v_cmp_gt_u32_e32 vcc, 0xe00, v3
	s_nop 1
	v_cndmask_b32_e32 v4, v4, v3, vcc
	global_load_dwordx4 v[16:19], v3, s[14:15] offset:0
	global_load_dwordx4 v[20:23], v3, s[14:15] offset:16
	global_load_dwordx4 v[24:27], v3, s[14:15] offset:32
	global_load_dwordx4 v[28:31], v3, s[14:15] offset:48
	global_load_dwordx4 v[32:35], v3, s[14:15] offset:64
	global_load_dwordx4 v[36:39], v3, s[14:15] offset:80
	global_load_dwordx4 v[40:43], v3, s[14:15] offset:96
	global_load_dwordx4 v[44:47], v3, s[14:15] offset:112
	global_load_dwordx4 v[48:51], v4, s[14:15] offset:0
	global_load_dwordx4 v[52:55], v4, s[14:15] offset:16
	global_load_dwordx4 v[56:59], v4, s[14:15] offset:32
	global_load_dwordx4 v[60:63], v4, s[14:15] offset:48
	global_load_dwordx4 v[64:67], v4, s[14:15] offset:64
	global_load_dwordx4 v[68:71], v4, s[14:15] offset:80
	global_load_dwordx4 v[72:75], v4, s[14:15] offset:96
	global_load_dwordx4 v[76:79], v4, s[14:15] offset:112
	global_load_dwordx4 v[80:83], v5, s[16:17] offset:0
	global_load_dwordx4 v[84:87], v5, s[16:17] offset:16
	global_load_dwordx4 v[88:91], v5, s[16:17] offset:32
	global_load_dwordx4 v[92:95], v5, s[16:17] offset:48
	global_load_dwordx4 v[96:99], v5, s[16:17] offset:64
	global_load_dwordx4 v[100:103], v5, s[16:17] offset:80
	global_load_dwordx4 v[104:107], v5, s[16:17] offset:96
	global_load_dwordx4 v[108:111], v5, s[16:17] offset:112
	global_load_dwordx4 v[112:115], v5, s[16:17] offset:128
	global_load_dwordx4 v[116:119], v5, s[16:17] offset:144
	global_load_dwordx4 v[120:123], v5, s[16:17] offset:160
	global_load_dwordx4 v[124:127], v5, s[16:17] offset:176
	global_load_dwordx4 v[128:131], v5, s[16:17] offset:192
	global_load_dwordx4 v[132:135], v5, s[16:17] offset:208
	global_load_dwordx4 v[136:139], v5, s[16:17] offset:224
	global_load_dwordx4 v[140:143], v5, s[16:17] offset:240
	s_sub_i32 s2, s26, 0x400
	s_mul_i32 s2, s2, 0x1c00
	s_add_i32 s2, s2, 0x1800
	v_add_u32_e32 v15, s2, v5
	s_cmp_eq_u32 s53, 0
	s_cbranch_scc1 .Llora_nsmp
	s_mov_b64 s[50:51], exec
	s_mov_b64 exec, 0xffff
	v_and_b32_e32 v12, 63, v180
	v_bfe_u32 v12, v12, 2, 2
	v_lshl_add_u32 v12, v12, 5, v15
	global_load_dwordx4 v[184:187], v12, s[18:19]
	global_load_dwordx4 v[188:191], v12, s[18:19] offset:16
	global_load_dwordx4 v[192:195], v12, s[18:19] offset:128
	global_load_dwordx4 v[196:199], v12, s[18:19] offset:144
	s_mov_b64 exec, s[50:51]
.Llora_nsmp:
	s_waitcnt vmcnt(0)
	v_lshlrev_b32_e32 v144, 16, v16
	v_and_b32_e32 v145, 0xffff0000, v16
	v_lshlrev_b32_e32 v152, 16, v48
	v_and_b32_e32 v153, 0xffff0000, v48
	v_lshlrev_b32_e32 v146, 16, v17
	v_and_b32_e32 v147, 0xffff0000, v17
	v_lshlrev_b32_e32 v154, 16, v49
	v_and_b32_e32 v155, 0xffff0000, v49
	v_lshlrev_b32_e32 v148, 16, v18
	v_and_b32_e32 v149, 0xffff0000, v18
	v_lshlrev_b32_e32 v156, 16, v50
	v_and_b32_e32 v157, 0xffff0000, v50
	v_lshlrev_b32_e32 v150, 16, v19
	v_and_b32_e32 v151, 0xffff0000, v19
	v_lshlrev_b32_e32 v158, 16, v51
	v_and_b32_e32 v159, 0xffff0000, v51
	s_cmp_eq_u32 s52, 0
	s_cbranch_scc1 .Llora_nf0
	s_mov_b64 s[50:51], exec
	s_mov_b64 exec, 15
	s_cmp_eq_u32 s53, 0
	s_cbranch_scc1 .Llora_pz0
	v_mov_b32_e32 v152, v184
	v_mov_b32_e32 v153, v185
	v_mov_b32_e32 v154, v186
	v_mov_b32_e32 v155, v187
	v_mov_b32_e32 v156, v188
	v_mov_b32_e32 v157, v189
	v_mov_b32_e32 v158, v190
	v_mov_b32_e32 v159, v191
	s_branch .Llora_pe0

; #define LAS __attribute__((address_space(3)))
; __device__ __forceinline__ unsigned pk2(float lo, float hi) { f32x2 v = {lo, hi}; bf16x2_t b = __builtin_convertvector(v, bf16x2_t); return __builtin_bit_cast(unsigned, b); }
; __device__ __forceinline__ float sigmoidf_(float x) { return frcp(1.f + fexp2(-1.4426950408889634f * x)); }
;     __device__ __forceinline__ const float* in(int i) const { return (const float*)ptr(i); }
; __device__ __forceinline__ void unpack8(const u32x4 w, float (&f)[8]) { f[0] = bflo(w.x); f[1] = bfhi(w.x); f[2] = bflo(w.y); f[3] = bfhi(w.y); f[4] = bflo(w.z); f[5] = bfhi(w.z); f[6] = bflo(w.w); f[7] = bfhi(w.w); }
; __device__ __forceinline__ void zshift8(const Ctx& p, const bf16_t* ZRW, int row, int c, const float (&mu)[8], float (&o)[8]) {
;     float z[8], pv[8];
;     unpack8(*(const u32x4*)(ZRW + (size_t)row * SHW + c), z);
;     bool first; int bsmp = 0;
;     if (row < MPR) first = (row & (TP - 1)) == 0; else { first = ((row - MPR) & 15) == 0; bsmp = (row - MPR) >> 4; }
;     if (!first) unpack8(*(const u32x4*)(ZRW + (size_t)(row - 1) * SHW + c), pv);
;     else if (row < MPR) {
; #pragma unroll
;         for (int e = 0; e < 8; ++e) pv[e] = 0.f;
;     } else { const float* s0 = p.in(5) + (size_t)bsmp * SHW + c;
; #pragma unroll
;         for (int e = 0; e < 8; ++e) pv[e] = s0[e]; }
; #pragma unroll
;     for (int e = 0; e < 8; ++e) o[e] = z[e] + (pv[e] - z[e]) * mu[e];
; __device__ __forceinline__ void phase_lora(const Ctx& p, LAS unsigned char* lds) {
;     ...
;                 float m8[8], z[8];
; #pragma unroll
;                 for (int e = 0; e < 8; ++e) m8[e] = mu[c + e];
;                 zshift8(p, ZRW, row, 1536 + c, m8, z);
; #pragma unroll
;                 for (int e = 0; e < 8; ++e) z[e] = cq == 0 ? tanhf(z[e]) : (cq == 1 ? z[e] : sigmoidf_(z[e]));
;                 u32x4 w; w.x = pk2(z[0], z[1]); w.y = pk2(z[2], z[3]); w.z = pk2(z[4], z[5]); w.w = pk2(z[6], z[7]);
;                 *(LAS u32x4*)(X + tt * 264 + c) = w;
.Llora_nf0:
	v_sub_f32_e32 v152, v152, v144
	v_sub_f32_e32 v153, v153, v145
	v_sub_f32_e32 v154, v154, v146
	v_sub_f32_e32 v155, v155, v147
	v_sub_f32_e32 v156, v156, v148
	v_sub_f32_e32 v157, v157, v149
	v_sub_f32_e32 v158, v158, v150
	v_sub_f32_e32 v159, v159, v151
	v_fmac_f32_e32 v144, v152, v80
	v_fmac_f32_e32 v145, v153, v81
	v_fmac_f32_e32 v146, v154, v82
	v_fmac_f32_e32 v147, v155, v83
	v_fmac_f32_e32 v148, v156, v84
	v_fmac_f32_e32 v149, v157, v85
	v_fmac_f32_e32 v150, v158, v86
	v_fmac_f32_e32 v151, v159, v87
	v_mul_f32_e32 v152, v7, v144
	v_mul_f32_e32 v153, v7, v145
	v_mul_f32_e32 v154, v7, v146
	v_mul_f32_e32 v155, v7, v147
	v_mul_f32_e32 v156, v7, v148
	v_mul_f32_e32 v157, v7, v149
	v_mul_f32_e32 v158, v7, v150
	v_mul_f32_e32 v159, v7, v151
	v_exp_f32_e32 v152, v152
	v_exp_f32_e32 v153, v153
	v_exp_f32_e32 v154, v154
	v_exp_f32_e32 v155, v155
	v_exp_f32_e32 v156, v156
	v_exp_f32_e32 v157, v157
	v_exp_f32_e32 v158, v158
	v_exp_f32_e32 v159, v159
	v_add_f32_e32 v152, 1.0, v152
	v_add_f32_e32 v153, 1.0, v153
	v_add_f32_e32 v154, 1.0, v154
	v_add_f32_e32 v155, 1.0, v155
	v_add_f32_e32 v156, 1.0, v156
	v_add_f32_e32 v157, 1.0, v157
	v_add_f32_e32 v158, 1.0, v158
	v_add_f32_e32 v159, 1.0, v159
	v_rcp_f32_e32 v152, v152
	v_rcp_f32_e32 v153, v153
	v_rcp_f32_e32 v154, v154
	v_rcp_f32_e32 v155, v155
	v_rcp_f32_e32 v156, v156
	v_rcp_f32_e32 v157, v157
	v_rcp_f32_e32 v158, v158
	v_rcp_f32_e32 v159, v159
	v_fma_f32 v152, v152, v8, v9
	v_fma_f32 v153, v153, v8, v9
	v_fma_f32 v154, v154, v8, v9
	v_fma_f32 v155, v155, v8, v9
	v_fma_f32 v156, v156, v8, v9
	v_fma_f32 v157, v157, v8, v9
	v_fma_f32 v158, v158, v8, v9
	v_fma_f32 v159, v159, v8, v9
	v_cndmask_b32_e64 v152, v152, v144, s[48:49]
	v_cndmask_b32_e64 v153, v153, v145, s[48:49]
	v_cndmask_b32_e64 v154, v154, v146, s[48:49]
	v_cndmask_b32_e64 v155, v155, v147, s[48:49]
	v_cndmask_b32_e64 v156, v156, v148, s[48:49]
	v_cndmask_b32_e64 v157, v157, v149, s[48:49]
	v_cndmask_b32_e64 v158, v158, v150, s[48:49]
	v_cndmask_b32_e64 v159, v159, v151, s[48:49]
	v_cvt_pk_bf16_f32 v160, v152, v153
	v_cvt_pk_bf16_f32 v161, v154, v155
	v_cvt_pk_bf16_f32 v162, v156, v157
	v_cvt_pk_bf16_f32 v163, v158, v159
	ds_write_b128 v6, v[160:163] offset:0
	v_lshlrev_b32_e32 v144, 16, v20
	v_and_b32_e32 v145, 0xffff0000, v20
	v_lshlrev_b32_e32 v152, 16, v52
	v_and_b32_e32 v153, 0xffff0000, v52
	v_lshlrev_b32_e32 v146, 16, v21
	v_and_b32_e32 v147, 0xffff0000, v21
	v_lshlrev_b32_e32 v154, 16, v53
	v_and_b32_e32 v155, 0xffff0000, v53
	v_lshlrev_b32_e32 v148, 16, v22
	v_and_b32_e32 v149, 0xffff0000, v22
	v_lshlrev_b32_e32 v156, 16, v54
	v_and_b32_e32 v157, 0xffff0000, v54
	v_lshlrev_b32_e32 v150, 16, v23
	v_and_b32_e32 v151, 0xffff0000, v23
	v_lshlrev_b32_e32 v158, 16, v55
	v_and_b32_e32 v159, 0xffff0000, v55
	s_cmp_eq_u32 s52, 0
	s_cbranch_scc1 .Llora_nf1
	s_mov_b64 s[50:51], exec
	s_mov_b64 exec, 15
	s_cmp_eq_u32 s53, 0
	s_cbranch_scc1 .Llora_pz1
	s_mov_b64 exec, 0xffff
	v_mov_b32_dpp v200, v184 row_shl:4 row_mask:0xf bank_mask:0xf
	v_mov_b32_dpp v201, v185 row_shl:4 row_mask:0xf bank_mask:0xf
	v_mov_b32_dpp v202, v186 row_shl:4 row_mask:0xf bank_mask:0xf
	v_mov_b32_dpp v203, v187 row_shl:4 row_mask:0xf bank_mask:0xf
	v_mov_b32_dpp v204, v188 row_shl:4 row_mask:0xf bank_mask:0xf
	v_mov_b32_dpp v205, v189 row_shl:4 row_mask:0xf bank_mask:0xf
	v_mov_b32_dpp v206, v190 row_shl:4 row_mask:0xf bank_mask:0xf
	v_mov_b32_dpp v207, v191 row_shl:4 row_mask:0xf bank_mask:0xf
	s_mov_b64 exec, 15
	v_mov_b32_e32 v152, v200
	v_mov_b32_e32 v153, v201
	v_mov_b32_e32 v154, v202
	v_mov_b32_e32 v155, v203
	v_mov_b32_e32 v156, v204
	v_mov_b32_e32 v157, v205
	v_mov_b32_e32 v158, v206
	v_mov_b32_e32 v159, v207
	s_branch .Llora_pe1

; #define LAS __attribute__((address_space(3)))
; __device__ __forceinline__ unsigned pk2(float lo, float hi) { f32x2 v = {lo, hi}; bf16x2_t b = __builtin_convertvector(v, bf16x2_t); return __builtin_bit_cast(unsigned, b); }
; __device__ __forceinline__ float sigmoidf_(float x) { return frcp(1.f + fexp2(-1.4426950408889634f * x)); }
;     __device__ __forceinline__ const float* in(int i) const { return (const float*)ptr(i); }
; __device__ __forceinline__ void unpack8(const u32x4 w, float (&f)[8]) { f[0] = bflo(w.x); f[1] = bfhi(w.x); f[2] = bflo(w.y); f[3] = bfhi(w.y); f[4] = bflo(w.z); f[5] = bfhi(w.z); f[6] = bflo(w.w); f[7] = bfhi(w.w); }
; __device__ __forceinline__ void zshift8(const Ctx& p, const bf16_t* ZRW, int row, int c, const float (&mu)[8], float (&o)[8]) {
;     float z[8], pv[8];
;     unpack8(*(const u32x4*)(ZRW + (size_t)row * SHW + c), z);
;     bool first; int bsmp = 0;
;     if (row < MPR) first = (row & (TP - 1)) == 0; else { first = ((row - MPR) & 15) == 0; bsmp = (row - MPR) >> 4; }
;     if (!first) unpack8(*(const u32x4*)(ZRW + (size_t)(row - 1) * SHW + c), pv);
;     else if (row < MPR) {
; #pragma unroll
;         for (int e = 0; e < 8; ++e) pv[e] = 0.f;
;     } else { const float* s0 = p.in(5) + (size_t)bsmp * SHW + c;
; #pragma unroll
;         for (int e = 0; e < 8; ++e) pv[e] = s0[e]; }
; #pragma unroll
;     for (int e = 0; e < 8; ++e) o[e] = z[e] + (pv[e] - z[e]) * mu[e];
; __device__ __forceinline__ void phase_lora(const Ctx& p, LAS unsigned char* lds) {
;     ...
;                 float m8[8], z[8];
; #pragma unroll
;                 for (int e = 0; e < 8; ++e) m8[e] = mu[c + e];
;                 zshift8(p, ZRW, row, 1536 + c, m8, z);
; #pragma unroll
;                 for (int e = 0; e < 8; ++e) z[e] = cq == 0 ? tanhf(z[e]) : (cq == 1 ? z[e] : sigmoidf_(z[e]));
;                 u32x4 w; w.x = pk2(z[0], z[1]); w.y = pk2(z[2], z[3]); w.z = pk2(z[4], z[5]); w.w = pk2(z[6], z[7]);
;                 *(LAS u32x4*)(X + tt * 264 + c) = w;
.Llora_nf1:
	v_sub_f32_e32 v152, v152, v144
	v_sub_f32_e32 v153, v153, v145
	v_sub_f32_e32 v154, v154, v146
	v_sub_f32_e32 v155, v155, v147
	v_sub_f32_e32 v156, v156, v148
	v_sub_f32_e32 v157, v157, v149
	v_sub_f32_e32 v158, v158, v150
	v_sub_f32_e32 v159, v159, v151
	v_fmac_f32_e32 v144, v152, v88
	v_fmac_f32_e32 v145, v153, v89
	v_fmac_f32_e32 v146, v154, v90
	v_fmac_f32_e32 v147, v155, v91
	v_fmac_f32_e32 v148, v156, v92
	v_fmac_f32_e32 v149, v157, v93
	v_fmac_f32_e32 v150, v158, v94
	v_fmac_f32_e32 v151, v159, v95
	v_mul_f32_e32 v152, v7, v144
	v_mul_f32_e32 v153, v7, v145
	v_mul_f32_e32 v154, v7, v146
	v_mul_f32_e32 v155, v7, v147
	v_mul_f32_e32 v156, v7, v148
	v_mul_f32_e32 v157, v7, v149
	v_mul_f32_e32 v158, v7, v150
	v_mul_f32_e32 v159, v7, v151
	v_exp_f32_e32 v152, v152
	v_exp_f32_e32 v153, v153
	v_exp_f32_e32 v154, v154
	v_exp_f32_e32 v155, v155
	v_exp_f32_e32 v156, v156
	v_exp_f32_e32 v157, v157
	v_exp_f32_e32 v158, v158
	v_exp_f32_e32 v159, v159
	v_add_f32_e32 v152, 1.0, v152
	v_add_f32_e32 v153, 1.0, v153
	v_add_f32_e32 v154, 1.0, v154
	v_add_f32_e32 v155, 1.0, v155
	v_add_f32_e32 v156, 1.0, v156
	v_add_f32_e32 v157, 1.0, v157
	v_add_f32_e32 v158, 1.0, v158
	v_add_f32_e32 v159, 1.0, v159
	v_rcp_f32_e32 v152, v152
	v_rcp_f32_e32 v153, v153
	v_rcp_f32_e32 v154, v154
	v_rcp_f32_e32 v155, v155
	v_rcp_f32_e32 v156, v156
	v_rcp_f32_e32 v157, v157
	v_rcp_f32_e32 v158, v158
	v_rcp_f32_e32 v159, v159
	v_fma_f32 v152, v152, v8, v9
	v_fma_f32 v153, v153, v8, v9
	v_fma_f32 v154, v154, v8, v9
	v_fma_f32 v155, v155, v8, v9
	v_fma_f32 v156, v156, v8, v9
	v_fma_f32 v157, v157, v8, v9
	v_fma_f32 v158, v158, v8, v9
	v_fma_f32 v159, v159, v8, v9
	v_cndmask_b32_e64 v152, v152, v144, s[48:49]
	v_cndmask_b32_e64 v153, v153, v145, s[48:49]
	v_cndmask_b32_e64 v154, v154, v146, s[48:49]
	v_cndmask_b32_e64 v155, v155, v147, s[48:49]
	v_cndmask_b32_e64 v156, v156, v148, s[48:49]
	v_cndmask_b32_e64 v157, v157, v149, s[48:49]
	v_cndmask_b32_e64 v158, v158, v150, s[48:49]
	v_cndmask_b32_e64 v159, v159, v151, s[48:49]
	v_cvt_pk_bf16_f32 v160, v152, v153
	v_cvt_pk_bf16_f32 v161, v154, v155
	v_cvt_pk_bf16_f32 v162, v156, v157
	v_cvt_pk_bf16_f32 v163, v158, v159
	ds_write_b128 v6, v[160:163] offset:16
	v_lshlrev_b32_e32 v144, 16, v24
	v_and_b32_e32 v145, 0xffff0000, v24
	v_lshlrev_b32_e32 v152, 16, v56
	v_and_b32_e32 v153, 0xffff0000, v56
	v_lshlrev_b32_e32 v146, 16, v25
	v_and_b32_e32 v147, 0xffff0000, v25
	v_lshlrev_b32_e32 v154, 16, v57
	v_and_b32_e32 v155, 0xffff0000, v57
	v_lshlrev_b32_e32 v148, 16, v26
	v_and_b32_e32 v149, 0xffff0000, v26
	v_lshlrev_b32_e32 v156, 16, v58
	v_and_b32_e32 v157, 0xffff0000, v58
	v_lshlrev_b32_e32 v150, 16, v27
	v_and_b32_e32 v151, 0xffff0000, v27
	v_lshlrev_b32_e32 v158, 16, v59
	v_and_b32_e32 v159, 0xffff0000, v59
	s_cmp_eq_u32 s52, 0
	s_cbranch_scc1 .Llora_nf2
	s_mov_b64 s[50:51], exec
	s_mov_b64 exec, 15
	s_cmp_eq_u32 s53, 0
	s_cbranch_scc1 .Llora_pz2
	s_mov_b64 exec, 0xffff
	v_mov_b32_dpp v200, v184 row_shl:8 row_mask:0xf bank_mask:0xf
	v_mov_b32_dpp v201, v185 row_shl:8 row_mask:0xf bank_mask:0xf
	v_mov_b32_dpp v202, v186 row_shl:8 row_mask:0xf bank_mask:0xf
	v_mov_b32_dpp v203, v187 row_shl:8 row_mask:0xf bank_mask:0xf
	v_mov_b32_dpp v204, v188 row_shl:8 row_mask:0xf bank_mask:0xf
	v_mov_b32_dpp v205, v189 row_shl:8 row_mask:0xf bank_mask:0xf
	v_mov_b32_dpp v206, v190 row_shl:8 row_mask:0xf bank_mask:0xf
	v_mov_b32_dpp v207, v191 row_shl:8 row_mask:0xf bank_mask:0xf
	s_mov_b64 exec, 15
	v_mov_b32_e32 v152, v200
	v_mov_b32_e32 v153, v201
	v_mov_b32_e32 v154, v202
	v_mov_b32_e32 v155, v203
	v_mov_b32_e32 v156, v204
	v_mov_b32_e32 v157, v205
	v_mov_b32_e32 v158, v206
	v_mov_b32_e32 v159, v207
	s_branch .Llora_pe2

; #define LAS __attribute__((address_space(3)))
; __device__ __forceinline__ unsigned pk2(float lo, float hi) { f32x2 v = {lo, hi}; bf16x2_t b = __builtin_convertvector(v, bf16x2_t); return __builtin_bit_cast(unsigned, b); }
; __device__ __forceinline__ float sigmoidf_(float x) { return frcp(1.f + fexp2(-1.4426950408889634f * x)); }
;     __device__ __forceinline__ const float* in(int i) const { return (const float*)ptr(i); }
; __device__ __forceinline__ void unpack8(const u32x4 w, float (&f)[8]) { f[0] = bflo(w.x); f[1] = bfhi(w.x); f[2] = bflo(w.y); f[3] = bfhi(w.y); f[4] = bflo(w.z); f[5] = bfhi(w.z); f[6] = bflo(w.w); f[7] = bfhi(w.w); }
; __device__ __forceinline__ void zshift8(const Ctx& p, const bf16_t* ZRW, int row, int c, const float (&mu)[8], float (&o)[8]) {
;     float z[8], pv[8];
;     unpack8(*(const u32x4*)(ZRW + (size_t)row * SHW + c), z);
;     bool first; int bsmp = 0;
;     if (row < MPR) first = (row & (TP - 1)) == 0; else { first = ((row - MPR) & 15) == 0; bsmp = (row - MPR) >> 4; }
;     if (!first) unpack8(*(const u32x4*)(ZRW + (size_t)(row - 1) * SHW + c), pv);
;     else if (row < MPR) {
; #pragma unroll
;         for (int e = 0; e < 8; ++e) pv[e] = 0.f;
;     } else { const float* s0 = p.in(5) + (size_t)bsmp * SHW + c;
; #pragma unroll
;         for (int e = 0; e < 8; ++e) pv[e] = s0[e]; }
; #pragma unroll
;     for (int e = 0; e < 8; ++e) o[e] = z[e] + (pv[e] - z[e]) * mu[e];
; __device__ __forceinline__ void phase_lora(const Ctx& p, LAS unsigned char* lds) {
;     ...
;                 float m8[8], z[8];
; #pragma unroll
;                 for (int e = 0; e < 8; ++e) m8[e] = mu[c + e];
;                 zshift8(p, ZRW, row, 1536 + c, m8, z);
; #pragma unroll
;                 for (int e = 0; e < 8; ++e) z[e] = cq == 0 ? tanhf(z[e]) : (cq == 1 ? z[e] : sigmoidf_(z[e]));
;                 u32x4 w; w.x = pk2(z[0], z[1]); w.y = pk2(z[2], z[3]); w.z = pk2(z[4], z[5]); w.w = pk2(z[6], z[7]);
;                 *(LAS u32x4*)(X + tt * 264 + c) = w;
.Llora_nf2:
	v_sub_f32_e32 v152, v152, v144
	v_sub_f32_e32 v153, v153, v145
	v_sub_f32_e32 v154, v154, v146
	v_sub_f32_e32 v155, v155, v147
	v_sub_f32_e32 v156, v156, v148
	v_sub_f32_e32 v157, v157, v149
	v_sub_f32_e32 v158, v158, v150
	v_sub_f32_e32 v159, v159, v151
	v_fmac_f32_e32 v144, v152, v96
	v_fmac_f32_e32 v145, v153, v97
	v_fmac_f32_e32 v146, v154, v98
	v_fmac_f32_e32 v147, v155, v99
	v_fmac_f32_e32 v148, v156, v100
	v_fmac_f32_e32 v149, v157, v101
	v_fmac_f32_e32 v150, v158, v102
	v_fmac_f32_e32 v151, v159, v103
	v_mul_f32_e32 v152, v7, v144
	v_mul_f32_e32 v153, v7, v145
	v_mul_f32_e32 v154, v7, v146
	v_mul_f32_e32 v155, v7, v147
	v_mul_f32_e32 v156, v7, v148
	v_mul_f32_e32 v157, v7, v149
	v_mul_f32_e32 v158, v7, v150
	v_mul_f32_e32 v159, v7, v151
	v_exp_f32_e32 v152, v152
	v_exp_f32_e32 v153, v153
	v_exp_f32_e32 v154, v154
	v_exp_f32_e32 v155, v155
	v_exp_f32_e32 v156, v156
	v_exp_f32_e32 v157, v157
	v_exp_f32_e32 v158, v158
	v_exp_f32_e32 v159, v159
	v_add_f32_e32 v152, 1.0, v152
	v_add_f32_e32 v153, 1.0, v153
	v_add_f32_e32 v154, 1.0, v154
	v_add_f32_e32 v155, 1.0, v155
	v_add_f32_e32 v156, 1.0, v156
	v_add_f32_e32 v157, 1.0, v157
	v_add_f32_e32 v158, 1.0, v158
	v_add_f32_e32 v159, 1.0, v159
	v_rcp_f32_e32 v152, v152
	v_rcp_f32_e32 v153, v153
	v_rcp_f32_e32 v154, v154
	v_rcp_f32_e32 v155, v155
	v_rcp_f32_e32 v156, v156
	v_rcp_f32_e32 v157, v157
	v_rcp_f32_e32 v158, v158
	v_rcp_f32_e32 v159, v159
	v_fma_f32 v152, v152, v8, v9
	v_fma_f32 v153, v153, v8, v9
	v_fma_f32 v154, v154, v8, v9
	v_fma_f32 v155, v155, v8, v9
	v_fma_f32 v156, v156, v8, v9
	v_fma_f32 v157, v157, v8, v9
	v_fma_f32 v158, v158, v8, v9
	v_fma_f32 v159, v159, v8, v9
	v_cndmask_b32_e64 v152, v152, v144, s[48:49]
	v_cndmask_b32_e64 v153, v153, v145, s[48:49]
	v_cndmask_b32_e64 v154, v154, v146, s[48:49]
	v_cndmask_b32_e64 v155, v155, v147, s[48:49]
	v_cndmask_b32_e64 v156, v156, v148, s[48:49]
	v_cndmask_b32_e64 v157, v157, v149, s[48:49]
	v_cndmask_b32_e64 v158, v158, v150, s[48:49]
	v_cndmask_b32_e64 v159, v159, v151, s[48:49]
	v_cvt_pk_bf16_f32 v160, v152, v153
	v_cvt_pk_bf16_f32 v161, v154, v155
	v_cvt_pk_bf16_f32 v162, v156, v157
	v_cvt_pk_bf16_f32 v163, v158, v159
	ds_write_b128 v6, v[160:163] offset:32
	v_lshlrev_b32_e32 v144, 16, v28
	v_and_b32_e32 v145, 0xffff0000, v28
	v_lshlrev_b32_e32 v152, 16, v60
	v_and_b32_e32 v153, 0xffff0000, v60
	v_lshlrev_b32_e32 v146, 16, v29
	v_and_b32_e32 v147, 0xffff0000, v29
	v_lshlrev_b32_e32 v154, 16, v61
	v_and_b32_e32 v155, 0xffff0000, v61
	v_lshlrev_b32_e32 v148, 16, v30
	v_and_b32_e32 v149, 0xffff0000, v30
	v_lshlrev_b32_e32 v156, 16, v62
	v_and_b32_e32 v157, 0xffff0000, v62
	v_lshlrev_b32_e32 v150, 16, v31
	v_and_b32_e32 v151, 0xffff0000, v31
	v_lshlrev_b32_e32 v158, 16, v63
	v_and_b32_e32 v159, 0xffff0000, v63
	s_cmp_eq_u32 s52, 0
	s_cbranch_scc1 .Llora_nf3
	s_mov_b64 s[50:51], exec
	s_mov_b64 exec, 15
	s_cmp_eq_u32 s53, 0
	s_cbranch_scc1 .Llora_pz3
	s_mov_b64 exec, 0xffff
	v_mov_b32_dpp v200, v184 row_shl:12 row_mask:0xf bank_mask:0xf
	v_mov_b32_dpp v201, v185 row_shl:12 row_mask:0xf bank_mask:0xf
	v_mov_b32_dpp v202, v186 row_shl:12 row_mask:0xf bank_mask:0xf
	v_mov_b32_dpp v203, v187 row_shl:12 row_mask:0xf bank_mask:0xf
	v_mov_b32_dpp v204, v188 row_shl:12 row_mask:0xf bank_mask:0xf
	v_mov_b32_dpp v205, v189 row_shl:12 row_mask:0xf bank_mask:0xf
	v_mov_b32_dpp v206, v190 row_shl:12 row_mask:0xf bank_mask:0xf
	v_mov_b32_dpp v207, v191 row_shl:12 row_mask:0xf bank_mask:0xf
	s_mov_b64 exec, 15
	v_mov_b32_e32 v152, v200
	v_mov_b32_e32 v153, v201
	v_mov_b32_e32 v154, v202
	v_mov_b32_e32 v155, v203
	v_mov_b32_e32 v156, v204
	v_mov_b32_e32 v157, v205
	v_mov_b32_e32 v158, v206
	v_mov_b32_e32 v159, v207
	s_branch .Llora_pe3

; #define LAS __attribute__((address_space(3)))
; __device__ __forceinline__ unsigned pk2(float lo, float hi) { f32x2 v = {lo, hi}; bf16x2_t b = __builtin_convertvector(v, bf16x2_t); return __builtin_bit_cast(unsigned, b); }
; __device__ __forceinline__ float sigmoidf_(float x) { return frcp(1.f + fexp2(-1.4426950408889634f * x)); }
;     __device__ __forceinline__ const float* in(int i) const { return (const float*)ptr(i); }
; __device__ __forceinline__ void unpack8(const u32x4 w, float (&f)[8]) { f[0] = bflo(w.x); f[1] = bfhi(w.x); f[2] = bflo(w.y); f[3] = bfhi(w.y); f[4] = bflo(w.z); f[5] = bfhi(w.z); f[6] = bflo(w.w); f[7] = bfhi(w.w); }
; __device__ __forceinline__ void zshift8(const Ctx& p, const bf16_t* ZRW, int row, int c, const float (&mu)[8], float (&o)[8]) {
;     float z[8], pv[8];
;     unpack8(*(const u32x4*)(ZRW + (size_t)row * SHW + c), z);
;     bool first; int bsmp = 0;
;     if (row < MPR) first = (row & (TP - 1)) == 0; else { first = ((row - MPR) & 15) == 0; bsmp = (row - MPR) >> 4; }
;     if (!first) unpack8(*(const u32x4*)(ZRW + (size_t)(row - 1) * SHW + c), pv);
;     else if (row < MPR) {
; #pragma unroll
;         for (int e = 0; e < 8; ++e) pv[e] = 0.f;
;     } else { const float* s0 = p.in(5) + (size_t)bsmp * SHW + c;
; #pragma unroll
;         for (int e = 0; e < 8; ++e) pv[e] = s0[e]; }
; #pragma unroll
;     for (int e = 0; e < 8; ++e) o[e] = z[e] + (pv[e] - z[e]) * mu[e];
; __device__ __forceinline__ void phase_lora(const Ctx& p, LAS unsigned char* lds) {
;     ...
;                 float m8[8], z[8];
; #pragma unroll
;                 for (int e = 0; e < 8; ++e) m8[e] = mu[c + e];
;                 zshift8(p, ZRW, row, 1536 + c, m8, z);
; #pragma unroll
;                 for (int e = 0; e < 8; ++e) z[e] = cq == 0 ? tanhf(z[e]) : (cq == 1 ? z[e] : sigmoidf_(z[e]));
;                 u32x4 w; w.x = pk2(z[0], z[1]); w.y = pk2(z[2], z[3]); w.z = pk2(z[4], z[5]); w.w = pk2(z[6], z[7]);
;                 *(LAS u32x4*)(X + tt * 264 + c) = w;
.Llora_nf3:
	v_sub_f32_e32 v152, v152, v144
	v_sub_f32_e32 v153, v153, v145
	v_sub_f32_e32 v154, v154, v146
	v_sub_f32_e32 v155, v155, v147
	v_sub_f32_e32 v156, v156, v148
	v_sub_f32_e32 v157, v157, v149
	v_sub_f32_e32 v158, v158, v150
	v_sub_f32_e32 v159, v159, v151
	v_fmac_f32_e32 v144, v152, v104
	v_fmac_f32_e32 v145, v153, v105
	v_fmac_f32_e32 v146, v154, v106
	v_fmac_f32_e32 v147, v155, v107
	v_fmac_f32_e32 v148, v156, v108
	v_fmac_f32_e32 v149, v157, v109
	v_fmac_f32_e32 v150, v158, v110
	v_fmac_f32_e32 v151, v159, v111
	v_mul_f32_e32 v152, v7, v144
	v_mul_f32_e32 v153, v7, v145
	v_mul_f32_e32 v154, v7, v146
	v_mul_f32_e32 v155, v7, v147
	v_mul_f32_e32 v156, v7, v148
	v_mul_f32_e32 v157, v7, v149
	v_mul_f32_e32 v158, v7, v150
	v_mul_f32_e32 v159, v7, v151
	v_exp_f32_e32 v152, v152
	v_exp_f32_e32 v153, v153
	v_exp_f32_e32 v154, v154
	v_exp_f32_e32 v155, v155
	v_exp_f32_e32 v156, v156
	v_exp_f32_e32 v157, v157
	v_exp_f32_e32 v158, v158
	v_exp_f32_e32 v159, v159
	v_add_f32_e32 v152, 1.0, v152
	v_add_f32_e32 v153, 1.0, v153
	v_add_f32_e32 v154, 1.0, v154
	v_add_f32_e32 v155, 1.0, v155
	v_add_f32_e32 v156, 1.0, v156
	v_add_f32_e32 v157, 1.0, v157
	v_add_f32_e32 v158, 1.0, v158
	v_add_f32_e32 v159, 1.0, v159
	v_rcp_f32_e32 v152, v152
	v_rcp_f32_e32 v153, v153
	v_rcp_f32_e32 v154, v154
	v_rcp_f32_e32 v155, v155
	v_rcp_f32_e32 v156, v156
	v_rcp_f32_e32 v157, v157
	v_rcp_f32_e32 v158, v158
	v_rcp_f32_e32 v159, v159
	v_fma_f32 v152, v152, v8, v9
	v_fma_f32 v153, v153, v8, v9
	v_fma_f32 v154, v154, v8, v9
	v_fma_f32 v155, v155, v8, v9
	v_fma_f32 v156, v156, v8, v9
	v_fma_f32 v157, v157, v8, v9
	v_fma_f32 v158, v158, v8, v9
	v_fma_f32 v159, v159, v8, v9
	v_cndmask_b32_e64 v152, v152, v144, s[48:49]
	v_cndmask_b32_e64 v153, v153, v145, s[48:49]
	v_cndmask_b32_e64 v154, v154, v146, s[48:49]
	v_cndmask_b32_e64 v155, v155, v147, s[48:49]
	v_cndmask_b32_e64 v156, v156, v148, s[48:49]
	v_cndmask_b32_e64 v157, v157, v149, s[48:49]
	v_cndmask_b32_e64 v158, v158, v150, s[48:49]
	v_cndmask_b32_e64 v159, v159, v151, s[48:49]
	v_cvt_pk_bf16_f32 v160, v152, v153
	v_cvt_pk_bf16_f32 v161, v154, v155
	v_cvt_pk_bf16_f32 v162, v156, v157
	v_cvt_pk_bf16_f32 v163, v158, v159
	ds_write_b128 v6, v[160:163] offset:48
	v_lshlrev_b32_e32 v144, 16, v32
	v_and_b32_e32 v145, 0xffff0000, v32
	v_lshlrev_b32_e32 v152, 16, v64
	v_and_b32_e32 v153, 0xffff0000, v64
	v_lshlrev_b32_e32 v146, 16, v33
	v_and_b32_e32 v147, 0xffff0000, v33
	v_lshlrev_b32_e32 v154, 16, v65
	v_and_b32_e32 v155, 0xffff0000, v65
	v_lshlrev_b32_e32 v148, 16, v34
	v_and_b32_e32 v149, 0xffff0000, v34
	v_lshlrev_b32_e32 v156, 16, v66
	v_and_b32_e32 v157, 0xffff0000, v66
	v_lshlrev_b32_e32 v150, 16, v35
	v_and_b32_e32 v151, 0xffff0000, v35
	v_lshlrev_b32_e32 v158, 16, v67
	v_and_b32_e32 v159, 0xffff0000, v67
	s_cmp_eq_u32 s52, 0
	s_cbranch_scc1 .Llora_nf4
	s_mov_b64 s[50:51], exec
	s_mov_b64 exec, 15
	s_cmp_eq_u32 s53, 0
	s_cbranch_scc1 .Llora_pz4
	v_mov_b32_e32 v152, v192
	v_mov_b32_e32 v153, v193
	v_mov_b32_e32 v154, v194
	v_mov_b32_e32 v155, v195
	v_mov_b32_e32 v156, v196
	v_mov_b32_e32 v157, v197
	v_mov_b32_e32 v158, v198
	v_mov_b32_e32 v159, v199
	s_branch .Llora_pe4

; #define LAS __attribute__((address_space(3)))
; __device__ __forceinline__ unsigned pk2(float lo, float hi) { f32x2 v = {lo, hi}; bf16x2_t b = __builtin_convertvector(v, bf16x2_t); return __builtin_bit_cast(unsigned, b); }
; __device__ __forceinline__ float sigmoidf_(float x) { return frcp(1.f + fexp2(-1.4426950408889634f * x)); }
;     __device__ __forceinline__ const float* in(int i) const { return (const float*)ptr(i); }
; __device__ __forceinline__ void unpack8(const u32x4 w, float (&f)[8]) { f[0] = bflo(w.x); f[1] = bfhi(w.x); f[2] = bflo(w.y); f[3] = bfhi(w.y); f[4] = bflo(w.z); f[5] = bfhi(w.z); f[6] = bflo(w.w); f[7] = bfhi(w.w); }
; __device__ __forceinline__ void zshift8(const Ctx& p, const bf16_t* ZRW, int row, int c, const float (&mu)[8], float (&o)[8]) {
;     float z[8], pv[8];
;     unpack8(*(const u32x4*)(ZRW + (size_t)row * SHW + c), z);
;     bool first; int bsmp = 0;
;     if (row < MPR) first = (row & (TP - 1)) == 0; else { first = ((row - MPR) & 15) == 0; bsmp = (row - MPR) >> 4; }
;     if (!first) unpack8(*(const u32x4*)(ZRW + (size_t)(row - 1) * SHW + c), pv);
;     else if (row < MPR) {
; #pragma unroll
;         for (int e = 0; e < 8; ++e) pv[e] = 0.f;
;     } else { const float* s0 = p.in(5) + (size_t)bsmp * SHW + c;
; #pragma unroll
;         for (int e = 0; e < 8; ++e) pv[e] = s0[e]; }
; #pragma unroll
;     for (int e = 0; e < 8; ++e) o[e] = z[e] + (pv[e] - z[e]) * mu[e];
; __device__ __forceinline__ void phase_lora(const Ctx& p, LAS unsigned char* lds) {
;     ...
;                 float m8[8], z[8];
; #pragma unroll
;                 for (int e = 0; e < 8; ++e) m8[e] = mu[c + e];
;                 zshift8(p, ZRW, row, 1536 + c, m8, z);
; #pragma unroll
;                 for (int e = 0; e < 8; ++e) z[e] = cq == 0 ? tanhf(z[e]) : (cq == 1 ? z[e] : sigmoidf_(z[e]));
;                 u32x4 w; w.x = pk2(z[0], z[1]); w.y = pk2(z[2], z[3]); w.z = pk2(z[4], z[5]); w.w = pk2(z[6], z[7]);
;                 *(LAS u32x4*)(X + tt * 264 + c) = w;
.Llora_nf4:
	v_sub_f32_e32 v152, v152, v144
	v_sub_f32_e32 v153, v153, v145
	v_sub_f32_e32 v154, v154, v146
	v_sub_f32_e32 v155, v155, v147
	v_sub_f32_e32 v156, v156, v148
	v_sub_f32_e32 v157, v157, v149
	v_sub_f32_e32 v158, v158, v150
	v_sub_f32_e32 v159, v159, v151
	v_fmac_f32_e32 v144, v152, v112
	v_fmac_f32_e32 v145, v153, v113
	v_fmac_f32_e32 v146, v154, v114
	v_fmac_f32_e32 v147, v155, v115
	v_fmac_f32_e32 v148, v156, v116
	v_fmac_f32_e32 v149, v157, v117
	v_fmac_f32_e32 v150, v158, v118
	v_fmac_f32_e32 v151, v159, v119
	v_mul_f32_e32 v152, v7, v144
	v_mul_f32_e32 v153, v7, v145
	v_mul_f32_e32 v154, v7, v146
	v_mul_f32_e32 v155, v7, v147
	v_mul_f32_e32 v156, v7, v148
	v_mul_f32_e32 v157, v7, v149
	v_mul_f32_e32 v158, v7, v150
	v_mul_f32_e32 v159, v7, v151
	v_exp_f32_e32 v152, v152
	v_exp_f32_e32 v153, v153
	v_exp_f32_e32 v154, v154
	v_exp_f32_e32 v155, v155
	v_exp_f32_e32 v156, v156
	v_exp_f32_e32 v157, v157
	v_exp_f32_e32 v158, v158
	v_exp_f32_e32 v159, v159
	v_add_f32_e32 v152, 1.0, v152
	v_add_f32_e32 v153, 1.0, v153
	v_add_f32_e32 v154, 1.0, v154
	v_add_f32_e32 v155, 1.0, v155
	v_add_f32_e32 v156, 1.0, v156
	v_add_f32_e32 v157, 1.0, v157
	v_add_f32_e32 v158, 1.0, v158
	v_add_f32_e32 v159, 1.0, v159
	v_rcp_f32_e32 v152, v152
	v_rcp_f32_e32 v153, v153
	v_rcp_f32_e32 v154, v154
	v_rcp_f32_e32 v155, v155
	v_rcp_f32_e32 v156, v156
	v_rcp_f32_e32 v157, v157
	v_rcp_f32_e32 v158, v158
	v_rcp_f32_e32 v159, v159
	v_fma_f32 v152, v152, v8, v9
	v_fma_f32 v153, v153, v8, v9
	v_fma_f32 v154, v154, v8, v9
	v_fma_f32 v155, v155, v8, v9
	v_fma_f32 v156, v156, v8, v9
	v_fma_f32 v157, v157, v8, v9
	v_fma_f32 v158, v158, v8, v9
	v_fma_f32 v159, v159, v8, v9
	v_cndmask_b32_e64 v152, v152, v144, s[48:49]
	v_cndmask_b32_e64 v153, v153, v145, s[48:49]
	v_cndmask_b32_e64 v154, v154, v146, s[48:49]
	v_cndmask_b32_e64 v155, v155, v147, s[48:49]
	v_cndmask_b32_e64 v156, v156, v148, s[48:49]
	v_cndmask_b32_e64 v157, v157, v149, s[48:49]
	v_cndmask_b32_e64 v158, v158, v150, s[48:49]
	v_cndmask_b32_e64 v159, v159, v151, s[48:49]
	v_cvt_pk_bf16_f32 v160, v152, v153
	v_cvt_pk_bf16_f32 v161, v154, v155
	v_cvt_pk_bf16_f32 v162, v156, v157
	v_cvt_pk_bf16_f32 v163, v158, v159
	ds_write_b128 v6, v[160:163] offset:64
	v_lshlrev_b32_e32 v144, 16, v36
	v_and_b32_e32 v145, 0xffff0000, v36
	v_lshlrev_b32_e32 v152, 16, v68
	v_and_b32_e32 v153, 0xffff0000, v68
	v_lshlrev_b32_e32 v146, 16, v37
	v_and_b32_e32 v147, 0xffff0000, v37
	v_lshlrev_b32_e32 v154, 16, v69
	v_and_b32_e32 v155, 0xffff0000, v69
	v_lshlrev_b32_e32 v148, 16, v38
	v_and_b32_e32 v149, 0xffff0000, v38
	v_lshlrev_b32_e32 v156, 16, v70
	v_and_b32_e32 v157, 0xffff0000, v70
	v_lshlrev_b32_e32 v150, 16, v39
	v_and_b32_e32 v151, 0xffff0000, v39
	v_lshlrev_b32_e32 v158, 16, v71
	v_and_b32_e32 v159, 0xffff0000, v71
	s_cmp_eq_u32 s52, 0
	s_cbranch_scc1 .Llora_nf5
	s_mov_b64 s[50:51], exec
	s_mov_b64 exec, 15
	s_cmp_eq_u32 s53, 0
	s_cbranch_scc1 .Llora_pz5
	s_mov_b64 exec, 0xffff
	v_mov_b32_dpp v200, v192 row_shl:4 row_mask:0xf bank_mask:0xf
	v_mov_b32_dpp v201, v193 row_shl:4 row_mask:0xf bank_mask:0xf
	v_mov_b32_dpp v202, v194 row_shl:4 row_mask:0xf bank_mask:0xf
	v_mov_b32_dpp v203, v195 row_shl:4 row_mask:0xf bank_mask:0xf
	v_mov_b32_dpp v204, v196 row_shl:4 row_mask:0xf bank_mask:0xf
	v_mov_b32_dpp v205, v197 row_shl:4 row_mask:0xf bank_mask:0xf
	v_mov_b32_dpp v206, v198 row_shl:4 row_mask:0xf bank_mask:0xf
	v_mov_b32_dpp v207, v199 row_shl:4 row_mask:0xf bank_mask:0xf
	s_mov_b64 exec, 15
	v_mov_b32_e32 v152, v200
	v_mov_b32_e32 v153, v201
	v_mov_b32_e32 v154, v202
	v_mov_b32_e32 v155, v203
	v_mov_b32_e32 v156, v204
	v_mov_b32_e32 v157, v205
	v_mov_b32_e32 v158, v206
	v_mov_b32_e32 v159, v207
	s_branch .Llora_pe5

; #define LAS __attribute__((address_space(3)))
; __device__ __forceinline__ unsigned pk2(float lo, float hi) { f32x2 v = {lo, hi}; bf16x2_t b = __builtin_convertvector(v, bf16x2_t); return __builtin_bit_cast(unsigned, b); }
; __device__ __forceinline__ float sigmoidf_(float x) { return frcp(1.f + fexp2(-1.4426950408889634f * x)); }
;     __device__ __forceinline__ const float* in(int i) const { return (const float*)ptr(i); }
; __device__ __forceinline__ void unpack8(const u32x4 w, float (&f)[8]) { f[0] = bflo(w.x); f[1] = bfhi(w.x); f[2] = bflo(w.y); f[3] = bfhi(w.y); f[4] = bflo(w.z); f[5] = bfhi(w.z); f[6] = bflo(w.w); f[7] = bfhi(w.w); }
; __device__ __forceinline__ void zshift8(const Ctx& p, const bf16_t* ZRW, int row, int c, const float (&mu)[8], float (&o)[8]) {
;     float z[8], pv[8];
;     unpack8(*(const u32x4*)(ZRW + (size_t)row * SHW + c), z);
;     bool first; int bsmp = 0;
;     if (row < MPR) first = (row & (TP - 1)) == 0; else { first = ((row - MPR) & 15) == 0; bsmp = (row - MPR) >> 4; }
;     if (!first) unpack8(*(const u32x4*)(ZRW + (size_t)(row - 1) * SHW + c), pv);
;     else if (row < MPR) {
; #pragma unroll
;         for (int e = 0; e < 8; ++e) pv[e] = 0.f;
;     } else { const float* s0 = p.in(5) + (size_t)bsmp * SHW + c;
; #pragma unroll
;         for (int e = 0; e < 8; ++e) pv[e] = s0[e]; }
; #pragma unroll
;     for (int e = 0; e < 8; ++e) o[e] = z[e] + (pv[e] - z[e]) * mu[e];
; __device__ __forceinline__ void phase_lora(const Ctx& p, LAS unsigned char* lds) {
;     ...
;                 float m8[8], z[8];
; #pragma unroll
;                 for (int e = 0; e < 8; ++e) m8[e] = mu[c + e];
;                 zshift8(p, ZRW, row, 1536 + c, m8, z);
; #pragma unroll
;                 for (int e = 0; e < 8; ++e) z[e] = cq == 0 ? tanhf(z[e]) : (cq == 1 ? z[e] : sigmoidf_(z[e]));
;                 u32x4 w; w.x = pk2(z[0], z[1]); w.y = pk2(z[2], z[3]); w.z = pk2(z[4], z[5]); w.w = pk2(z[6], z[7]);
;                 *(LAS u32x4*)(X + tt * 264 + c) = w;
.Llora_nf5:
	v_sub_f32_e32 v152, v152, v144
	v_sub_f32_e32 v153, v153, v145
	v_sub_f32_e32 v154, v154, v146
	v_sub_f32_e32 v155, v155, v147
	v_sub_f32_e32 v156, v156, v148
	v_sub_f32_e32 v157, v157, v149
	v_sub_f32_e32 v158, v158, v150
	v_sub_f32_e32 v159, v159, v151
	v_fmac_f32_e32 v144, v152, v120
	v_fmac_f32_e32 v145, v153, v121
	v_fmac_f32_e32 v146, v154, v122
	v_fmac_f32_e32 v147, v155, v123
	v_fmac_f32_e32 v148, v156, v124
	v_fmac_f32_e32 v149, v157, v125
	v_fmac_f32_e32 v150, v158, v126
	v_fmac_f32_e32 v151, v159, v127
	v_mul_f32_e32 v152, v7, v144
	v_mul_f32_e32 v153, v7, v145
	v_mul_f32_e32 v154, v7, v146
	v_mul_f32_e32 v155, v7, v147
	v_mul_f32_e32 v156, v7, v148
	v_mul_f32_e32 v157, v7, v149
	v_mul_f32_e32 v158, v7, v150
	v_mul_f32_e32 v159, v7, v151
	v_exp_f32_e32 v152, v152
	v_exp_f32_e32 v153, v153
	v_exp_f32_e32 v154, v154
	v_exp_f32_e32 v155, v155
	v_exp_f32_e32 v156, v156
	v_exp_f32_e32 v157, v157
	v_exp_f32_e32 v158, v158
	v_exp_f32_e32 v159, v159
	v_add_f32_e32 v152, 1.0, v152
	v_add_f32_e32 v153, 1.0, v153
	v_add_f32_e32 v154, 1.0, v154
	v_add_f32_e32 v155, 1.0, v155
	v_add_f32_e32 v156, 1.0, v156
	v_add_f32_e32 v157, 1.0, v157
	v_add_f32_e32 v158, 1.0, v158
	v_add_f32_e32 v159, 1.0, v159
	v_rcp_f32_e32 v152, v152
	v_rcp_f32_e32 v153, v153
	v_rcp_f32_e32 v154, v154
	v_rcp_f32_e32 v155, v155
	v_rcp_f32_e32 v156, v156
	v_rcp_f32_e32 v157, v157
	v_rcp_f32_e32 v158, v158
	v_rcp_f32_e32 v159, v159
	v_fma_f32 v152, v152, v8, v9
	v_fma_f32 v153, v153, v8, v9
	v_fma_f32 v154, v154, v8, v9
	v_fma_f32 v155, v155, v8, v9
	v_fma_f32 v156, v156, v8, v9
	v_fma_f32 v157, v157, v8, v9
	v_fma_f32 v158, v158, v8, v9
	v_fma_f32 v159, v159, v8, v9
	v_cndmask_b32_e64 v152, v152, v144, s[48:49]
	v_cndmask_b32_e64 v153, v153, v145, s[48:49]
	v_cndmask_b32_e64 v154, v154, v146, s[48:49]
	v_cndmask_b32_e64 v155, v155, v147, s[48:49]
	v_cndmask_b32_e64 v156, v156, v148, s[48:49]
	v_cndmask_b32_e64 v157, v157, v149, s[48:49]
	v_cndmask_b32_e64 v158, v158, v150, s[48:49]
	v_cndmask_b32_e64 v159, v159, v151, s[48:49]
	v_cvt_pk_bf16_f32 v160, v152, v153
	v_cvt_pk_bf16_f32 v161, v154, v155
	v_cvt_pk_bf16_f32 v162, v156, v157
	v_cvt_pk_bf16_f32 v163, v158, v159
	ds_write_b128 v6, v[160:163] offset:80
	v_lshlrev_b32_e32 v144, 16, v40
	v_and_b32_e32 v145, 0xffff0000, v40
	v_lshlrev_b32_e32 v152, 16, v72
	v_and_b32_e32 v153, 0xffff0000, v72
	v_lshlrev_b32_e32 v146, 16, v41
	v_and_b32_e32 v147, 0xffff0000, v41
	v_lshlrev_b32_e32 v154, 16, v73
	v_and_b32_e32 v155, 0xffff0000, v73
	v_lshlrev_b32_e32 v148, 16, v42
	v_and_b32_e32 v149, 0xffff0000, v42
	v_lshlrev_b32_e32 v156, 16, v74
	v_and_b32_e32 v157, 0xffff0000, v74
	v_lshlrev_b32_e32 v150, 16, v43
	v_and_b32_e32 v151, 0xffff0000, v43
	v_lshlrev_b32_e32 v158, 16, v75
	v_and_b32_e32 v159, 0xffff0000, v75
	s_cmp_eq_u32 s52, 0
	s_cbranch_scc1 .Llora_nf6
	s_mov_b64 s[50:51], exec
	s_mov_b64 exec, 15
	s_cmp_eq_u32 s53, 0
	s_cbranch_scc1 .Llora_pz6
	s_mov_b64 exec, 0xffff
	v_mov_b32_dpp v200, v192 row_shl:8 row_mask:0xf bank_mask:0xf
	v_mov_b32_dpp v201, v193 row_shl:8 row_mask:0xf bank_mask:0xf
	v_mov_b32_dpp v202, v194 row_shl:8 row_mask:0xf bank_mask:0xf
	v_mov_b32_dpp v203, v195 row_shl:8 row_mask:0xf bank_mask:0xf
	v_mov_b32_dpp v204, v196 row_shl:8 row_mask:0xf bank_mask:0xf
	v_mov_b32_dpp v205, v197 row_shl:8 row_mask:0xf bank_mask:0xf
	v_mov_b32_dpp v206, v198 row_shl:8 row_mask:0xf bank_mask:0xf
	v_mov_b32_dpp v207, v199 row_shl:8 row_mask:0xf bank_mask:0xf
	s_mov_b64 exec, 15
	v_mov_b32_e32 v152, v200
	v_mov_b32_e32 v153, v201
	v_mov_b32_e32 v154, v202
	v_mov_b32_e32 v155, v203
	v_mov_b32_e32 v156, v204
	v_mov_b32_e32 v157, v205
	v_mov_b32_e32 v158, v206
	v_mov_b32_e32 v159, v207
	s_branch .Llora_pe6

; #define LAS __attribute__((address_space(3)))
; __device__ __forceinline__ unsigned pk2(float lo, float hi) { f32x2 v = {lo, hi}; bf16x2_t b = __builtin_convertvector(v, bf16x2_t); return __builtin_bit_cast(unsigned, b); }
; __device__ __forceinline__ float sigmoidf_(float x) { return frcp(1.f + fexp2(-1.4426950408889634f * x)); }
;     __device__ __forceinline__ const float* in(int i) const { return (const float*)ptr(i); }
; __device__ __forceinline__ void unpack8(const u32x4 w, float (&f)[8]) { f[0] = bflo(w.x); f[1] = bfhi(w.x); f[2] = bflo(w.y); f[3] = bfhi(w.y); f[4] = bflo(w.z); f[5] = bfhi(w.z); f[6] = bflo(w.w); f[7] = bfhi(w.w); }
; __device__ __forceinline__ void zshift8(const Ctx& p, const bf16_t* ZRW, int row, int c, const float (&mu)[8], float (&o)[8]) {
;     float z[8], pv[8];
;     unpack8(*(const u32x4*)(ZRW + (size_t)row * SHW + c), z);
;     bool first; int bsmp = 0;
;     if (row < MPR) first = (row & (TP - 1)) == 0; else { first = ((row - MPR) & 15) == 0; bsmp = (row - MPR) >> 4; }
;     if (!first) unpack8(*(const u32x4*)(ZRW + (size_t)(row - 1) * SHW + c), pv);
;     else if (row < MPR) {
; #pragma unroll
;         for (int e = 0; e < 8; ++e) pv[e] = 0.f;
;     } else { const float* s0 = p.in(5) + (size_t)bsmp * SHW + c;
; #pragma unroll
;         for (int e = 0; e < 8; ++e) pv[e] = s0[e]; }
; #pragma unroll
;     for (int e = 0; e < 8; ++e) o[e] = z[e] + (pv[e] - z[e]) * mu[e];
; __device__ __forceinline__ void phase_lora(const Ctx& p, LAS unsigned char* lds) {
;     ...
;                 float m8[8], z[8];
; #pragma unroll
;                 for (int e = 0; e < 8; ++e) m8[e] = mu[c + e];
;                 zshift8(p, ZRW, row, 1536 + c, m8, z);
; #pragma unroll
;                 for (int e = 0; e < 8; ++e) z[e] = cq == 0 ? tanhf(z[e]) : (cq == 1 ? z[e] : sigmoidf_(z[e]));
;                 u32x4 w; w.x = pk2(z[0], z[1]); w.y = pk2(z[2], z[3]); w.z = pk2(z[4], z[5]); w.w = pk2(z[6], z[7]);
;                 *(LAS u32x4*)(X + tt * 264 + c) = w;
.Llora_nf6:
	v_sub_f32_e32 v152, v152, v144
	v_sub_f32_e32 v153, v153, v145
	v_sub_f32_e32 v154, v154, v146
	v_sub_f32_e32 v155, v155, v147
	v_sub_f32_e32 v156, v156, v148
	v_sub_f32_e32 v157, v157, v149
	v_sub_f32_e32 v158, v158, v150
	v_sub_f32_e32 v159, v159, v151
	v_fmac_f32_e32 v144, v152, v128
	v_fmac_f32_e32 v145, v153, v129
	v_fmac_f32_e32 v146, v154, v130
	v_fmac_f32_e32 v147, v155, v131
	v_fmac_f32_e32 v148, v156, v132
	v_fmac_f32_e32 v149, v157, v133
	v_fmac_f32_e32 v150, v158, v134
	v_fmac_f32_e32 v151, v159, v135
	v_mul_f32_e32 v152, v7, v144
	v_mul_f32_e32 v153, v7, v145
	v_mul_f32_e32 v154, v7, v146
	v_mul_f32_e32 v155, v7, v147
	v_mul_f32_e32 v156, v7, v148
	v_mul_f32_e32 v157, v7, v149
	v_mul_f32_e32 v158, v7, v150
	v_mul_f32_e32 v159, v7, v151
	v_exp_f32_e32 v152, v152
	v_exp_f32_e32 v153, v153
	v_exp_f32_e32 v154, v154
	v_exp_f32_e32 v155, v155
	v_exp_f32_e32 v156, v156
	v_exp_f32_e32 v157, v157
	v_exp_f32_e32 v158, v158
	v_exp_f32_e32 v159, v159
	v_add_f32_e32 v152, 1.0, v152
	v_add_f32_e32 v153, 1.0, v153
	v_add_f32_e32 v154, 1.0, v154
	v_add_f32_e32 v155, 1.0, v155
	v_add_f32_e32 v156, 1.0, v156
	v_add_f32_e32 v157, 1.0, v157
	v_add_f32_e32 v158, 1.0, v158
	v_add_f32_e32 v159, 1.0, v159
	v_rcp_f32_e32 v152, v152
	v_rcp_f32_e32 v153, v153
	v_rcp_f32_e32 v154, v154
	v_rcp_f32_e32 v155, v155
	v_rcp_f32_e32 v156, v156
	v_rcp_f32_e32 v157, v157
	v_rcp_f32_e32 v158, v158
	v_rcp_f32_e32 v159, v159
	v_fma_f32 v152, v152, v8, v9
	v_fma_f32 v153, v153, v8, v9
	v_fma_f32 v154, v154, v8, v9
	v_fma_f32 v155, v155, v8, v9
	v_fma_f32 v156, v156, v8, v9
	v_fma_f32 v157, v157, v8, v9
	v_fma_f32 v158, v158, v8, v9
	v_fma_f32 v159, v159, v8, v9
	v_cndmask_b32_e64 v152, v152, v144, s[48:49]
	v_cndmask_b32_e64 v153, v153, v145, s[48:49]
	v_cndmask_b32_e64 v154, v154, v146, s[48:49]
	v_cndmask_b32_e64 v155, v155, v147, s[48:49]
	v_cndmask_b32_e64 v156, v156, v148, s[48:49]
	v_cndmask_b32_e64 v157, v157, v149, s[48:49]
	v_cndmask_b32_e64 v158, v158, v150, s[48:49]
	v_cndmask_b32_e64 v159, v159, v151, s[48:49]
	v_cvt_pk_bf16_f32 v160, v152, v153
	v_cvt_pk_bf16_f32 v161, v154, v155
	v_cvt_pk_bf16_f32 v162, v156, v157
	v_cvt_pk_bf16_f32 v163, v158, v159
	ds_write_b128 v6, v[160:163] offset:96
	v_lshlrev_b32_e32 v144, 16, v44
	v_and_b32_e32 v145, 0xffff0000, v44
	v_lshlrev_b32_e32 v152, 16, v76
	v_and_b32_e32 v153, 0xffff0000, v76
	v_lshlrev_b32_e32 v146, 16, v45
	v_and_b32_e32 v147, 0xffff0000, v45
	v_lshlrev_b32_e32 v154, 16, v77
	v_and_b32_e32 v155, 0xffff0000, v77
	v_lshlrev_b32_e32 v148, 16, v46
	v_and_b32_e32 v149, 0xffff0000, v46
	v_lshlrev_b32_e32 v156, 16, v78
	v_and_b32_e32 v157, 0xffff0000, v78
	v_lshlrev_b32_e32 v150, 16, v47
	v_and_b32_e32 v151, 0xffff0000, v47
	v_lshlrev_b32_e32 v158, 16, v79
	v_and_b32_e32 v159, 0xffff0000, v79
	s_cmp_eq_u32 s52, 0
	s_cbranch_scc1 .Llora_nf7
	s_mov_b64 s[50:51], exec
	s_mov_b64 exec, 15
	s_cmp_eq_u32 s53, 0
	s_cbranch_scc1 .Llora_pz7
	s_mov_b64 exec, 0xffff
	v_mov_b32_dpp v200, v192 row_shl:12 row_mask:0xf bank_mask:0xf
	v_mov_b32_dpp v201, v193 row_shl:12 row_mask:0xf bank_mask:0xf
	v_mov_b32_dpp v202, v194 row_shl:12 row_mask:0xf bank_mask:0xf
	v_mov_b32_dpp v203, v195 row_shl:12 row_mask:0xf bank_mask:0xf
	v_mov_b32_dpp v204, v196 row_shl:12 row_mask:0xf bank_mask:0xf
	v_mov_b32_dpp v205, v197 row_shl:12 row_mask:0xf bank_mask:0xf
	v_mov_b32_dpp v206, v198 row_shl:12 row_mask:0xf bank_mask:0xf
	v_mov_b32_dpp v207, v199 row_shl:12 row_mask:0xf bank_mask:0xf
	s_mov_b64 exec, 15
	v_mov_b32_e32 v152, v200
	v_mov_b32_e32 v153, v201
	v_mov_b32_e32 v154, v202
	v_mov_b32_e32 v155, v203
	v_mov_b32_e32 v156, v204
	v_mov_b32_e32 v157, v205
	v_mov_b32_e32 v158, v206
	v_mov_b32_e32 v159, v207
	s_branch .Llora_pe7

; #define LAS __attribute__((address_space(3)))
; __device__ __forceinline__ unsigned pk2(float lo, float hi) { f32x2 v = {lo, hi}; bf16x2_t b = __builtin_convertvector(v, bf16x2_t); return __builtin_bit_cast(unsigned, b); }
; __device__ __forceinline__ float sigmoidf_(float x) { return frcp(1.f + fexp2(-1.4426950408889634f * x)); }
;     __device__ __forceinline__ const float* in(int i) const { return (const float*)ptr(i); }
; __device__ __forceinline__ void phase_lora(const Ctx& p, LAS unsigned char* lds) {
;     ...
;                 float m8[8], z[8];
; #pragma unroll
;                 for (int e = 0; e < 8; ++e) m8[e] = mu[c + e];
;                 zshift8(p, ZRW, row, 1536 + c, m8, z);
; #pragma unroll
;                 for (int e = 0; e < 8; ++e) z[e] = cq == 0 ? tanhf(z[e]) : (cq == 1 ? z[e] : sigmoidf_(z[e]));
;                 u32x4 w; w.x = pk2(z[0], z[1]); w.y = pk2(z[2], z[3]); w.z = pk2(z[4], z[5]); w.w = pk2(z[6], z[7]);
;                 *(LAS u32x4*)(X + tt * 264 + c) = w;
;             }
;         }
;         asm volatile("s_waitcnt lgkmcnt(0)" ::: "memory");
;         bf16x8 bx[8];
; #pragma unroll
;         for (int ks = 0; ks < 8; ++ks) bx[ks] = *(const LAS bf16x8*)(X + q * 264 + ks * 32 + 8 * g);
;         const int row = r0 + q;
;         struct WF { bf16x8 w[2], a[2], gq[4]; f32x4 w0, a0; };
;         auto ldw = [&](WF& f, int nt) {
;             const int n = nt * 16 + q, c = nt * 16 + 4 * g;
; #pragma unroll
;             for (int ks = 0; ks < 2; ++ks) { f.w[ks] = *(const bf16x8*)(w2T + n * 64 + ks * 32 + 8 * g); f.a[ks] = *(const bf16x8*)(a2T + n * 64 + ks * 32 + 8 * g); }
; #pragma unroll
;             for (int ks = 0; ks < 4; ++ks) f.gq[ks] = *(const bf16x8*)(g2T + n * 128 + ks * 32 + 8 * g);
;             f.w0 = *(const f32x4*)(p.in(18) + c); f.a0 = *(const f32x4*)(p.in(20) + c);
;         };
.Llora_nf7:
	v_sub_f32_e32 v152, v152, v144
	v_sub_f32_e32 v153, v153, v145
	v_sub_f32_e32 v154, v154, v146
	v_sub_f32_e32 v155, v155, v147
	v_sub_f32_e32 v156, v156, v148
	v_sub_f32_e32 v157, v157, v149
	v_sub_f32_e32 v158, v158, v150
	v_sub_f32_e32 v159, v159, v151
	v_fmac_f32_e32 v144, v152, v136
	v_fmac_f32_e32 v145, v153, v137
	v_fmac_f32_e32 v146, v154, v138
	v_fmac_f32_e32 v147, v155, v139
	v_fmac_f32_e32 v148, v156, v140
	v_fmac_f32_e32 v149, v157, v141
	v_fmac_f32_e32 v150, v158, v142
	v_fmac_f32_e32 v151, v159, v143
	v_mul_f32_e32 v152, v7, v144
	v_mul_f32_e32 v153, v7, v145
	v_mul_f32_e32 v154, v7, v146
	v_mul_f32_e32 v155, v7, v147
	v_mul_f32_e32 v156, v7, v148
	v_mul_f32_e32 v157, v7, v149
	v_mul_f32_e32 v158, v7, v150
	v_mul_f32_e32 v159, v7, v151
	v_exp_f32_e32 v152, v152
	v_exp_f32_e32 v153, v153
	v_exp_f32_e32 v154, v154
	v_exp_f32_e32 v155, v155
	v_exp_f32_e32 v156, v156
	v_exp_f32_e32 v157, v157
	v_exp_f32_e32 v158, v158
	v_exp_f32_e32 v159, v159
	v_add_f32_e32 v152, 1.0, v152
	v_add_f32_e32 v153, 1.0, v153
	v_add_f32_e32 v154, 1.0, v154
	v_add_f32_e32 v155, 1.0, v155
	v_add_f32_e32 v156, 1.0, v156
	v_add_f32_e32 v157, 1.0, v157
	v_add_f32_e32 v158, 1.0, v158
	v_add_f32_e32 v159, 1.0, v159
	v_rcp_f32_e32 v152, v152
	v_rcp_f32_e32 v153, v153
	v_rcp_f32_e32 v154, v154
	v_rcp_f32_e32 v155, v155
	v_rcp_f32_e32 v156, v156
	v_rcp_f32_e32 v157, v157
	v_rcp_f32_e32 v158, v158
	v_rcp_f32_e32 v159, v159
	v_fma_f32 v152, v152, v8, v9
	v_fma_f32 v153, v153, v8, v9
	v_fma_f32 v154, v154, v8, v9
	v_fma_f32 v155, v155, v8, v9
	v_fma_f32 v156, v156, v8, v9
	v_fma_f32 v157, v157, v8, v9
	v_fma_f32 v158, v158, v8, v9
	v_fma_f32 v159, v159, v8, v9
	v_cndmask_b32_e64 v152, v152, v144, s[48:49]
	v_cndmask_b32_e64 v153, v153, v145, s[48:49]
	v_cndmask_b32_e64 v154, v154, v146, s[48:49]
	v_cndmask_b32_e64 v155, v155, v147, s[48:49]
	v_cndmask_b32_e64 v156, v156, v148, s[48:49]
	v_cndmask_b32_e64 v157, v157, v149, s[48:49]
	v_cndmask_b32_e64 v158, v158, v150, s[48:49]
	v_cndmask_b32_e64 v159, v159, v151, s[48:49]
	v_cvt_pk_bf16_f32 v160, v152, v153
	v_cvt_pk_bf16_f32 v161, v154, v155
	v_cvt_pk_bf16_f32 v162, v156, v157
	v_cvt_pk_bf16_f32 v163, v158, v159
	ds_write_b128 v6, v[160:163] offset:112
	s_waitcnt lgkmcnt(0)
	ds_read_b128 v[184:187], v14 offset:0
	ds_read_b128 v[188:191], v14 offset:64
	ds_read_b128 v[192:195], v14 offset:128
	ds_read_b128 v[196:199], v14 offset:192
	ds_read_b128 v[200:203], v14 offset:256
	ds_read_b128 v[204:207], v14 offset:320
	ds_read_b128 v[208:211], v14 offset:384
	ds_read_b128 v[212:215], v14 offset:448
	s_lshl_b32 s2, s26, 4
	v_add_u32_e32 v137, s2, v10
	v_lshl_add_u32 v132, v11, 4, v10
	v_lshlrev_b32_e32 v132, 4, v132
	v_mov_b32_e32 v133, v132
	v_lshlrev_b32_e32 v134, 4, v11
	v_lshlrev_b32_e32 v135, 11, v137
	v_lshl_add_u32 v135, v11, 4, v135
	v_lshlrev_b32_e32 v136, 10, v137
	v_lshl_add_u32 v136, v11, 3, v136
	s_cmp_lg_u32 s57, 0
	s_cbranch_scc1 .Llora_single
	s_lshl_b32 s2, s56, 15
	v_add_u32_e32 v132, s2, v132
	s_lshl_b32 s2, s56, 16
	v_add_u32_e32 v133, s2, v133
	s_lshl_b32 s2, s56, 10
	v_add_u32_e32 v134, s2, v134
	v_add_u32_e32 v135, s2, v135
	s_lshl_b32 s2, s56, 9
	v_add_u32_e32 v136, s2, v136
	s_and_b32 s60, s27, 3
	s_cmp_gt_u32 s60, 1
	s_cselect_b32 s3, 1, 0
	s_movk_i32 s64, 0x800
	s_lshl_b32 s64, s64, s3
	s_lshl_b32 s2, s60, 16
	s_cmp_eq_u32 s60, 2
	s_cselect_b32 s2, 0x20000, s2
	s_cmp_eq_u32 s60, 3
	s_cselect_b32 s2, 0x20800, s2
	s_lshl_b32 s3, s64, 4
	s_mul_i32 s3, s3, s56
	s_add_u32 s2, s2, s3
	s_add_u32 s62, s24, s2
	s_addc_u32 s63, s25, 0
	s_lshl_b32 s2, s56, 13
	s_lshl_b32 s3, s60, 11
	s_add_i32 s2, s2, s3
	s_add_i32 s60, s2, 0x10800
	v_lshl_add_u32 v138, v11, 4, v10
	v_lshlrev_b32_e32 v138, 4, v138
	v_add_u32_e32 v139, 0x400, v138
	v_add_u32_e32 v144, s60, v138
	s_lshl_b32 s2, s56, 13
	v_add_u32_e32 v140, s2, v138
	v_add_u32_e32 v140, 0x10800, v140
	v_lshlrev_b32_e32 v141, 2, v180
	global_load_dword v142, v141, s[20:21]
	global_load_dword v143, v141, s[22:23]
	v_add_u32_e32 v134, 0x1c800, v134
	v_add_u32_e32 v141, 0x1c800, v141
	global_load_dwordx4 v[56:59], v138, s[62:63]
	global_load_dwordx4 v[60:63], v139, s[62:63]
	s_add_u32 s62, s62, s64
	s_addc_u32 s63, s63, 0
	global_load_dwordx4 v[64:67], v138, s[62:63]
	global_load_dwordx4 v[68:71], v139, s[62:63]
	s_add_u32 s62, s62, s64
	s_addc_u32 s63, s63, 0
	s_waitcnt vmcnt(4)
	ds_write_b32 v141, v142
	ds_write_b32 v141, v143 offset:2048
	s_waitcnt vmcnt(2)
	ds_write_b128 v144, v[56:59] offset:0
	ds_write_b128 v144, v[60:63] offset:1024
	s_waitcnt lgkmcnt(0)
	s_barrier
; __device__ __forceinline__ unsigned pk2(float lo, float hi) { f32x2 v = {lo, hi}; bf16x2_t b = __builtin_convertvector(v, bf16x2_t); return __builtin_bit_cast(unsigned, b); }
; __device__ __forceinline__ float sigmoidf_(float x) { return frcp(1.f + fexp2(-1.4426950408889634f * x)); }
;     __device__ __forceinline__ const float* in(int i) const { return (const float*)ptr(i); }
; __device__ __forceinline__ void phase_lora(const Ctx& p, LAS unsigned char* lds) {
;     ...
;         auto ldw = [&](WF& f, int nt) {
;             const int n = nt * 16 + q, c = nt * 16 + 4 * g;
; #pragma unroll
;             for (int ks = 0; ks < 2; ++ks) { f.w[ks] = *(const bf16x8*)(w2T + n * 64 + ks * 32 + 8 * g); f.a[ks] = *(const bf16x8*)(a2T + n * 64 + ks * 32 + 8 * g); }
; #pragma unroll
;             for (int ks = 0; ks < 4; ++ks) f.gq[ks] = *(const bf16x8*)(g2T + n * 128 + ks * 32 + 8 * g);
;             f.w0 = *(const f32x4*)(p.in(18) + c); f.a0 = *(const f32x4*)(p.in(20) + c);
;         };
;         auto tile = [&](const WF& f, int nt) {
;             f32x4 aw = (f32x4){0.f, 0.f, 0.f, 0.f}, aa = aw, ag = aw;
; #pragma unroll
;             for (int ks = 0; ks < 2; ++ks) { aw = __builtin_amdgcn_mfma_f32_16x16x32_bf16(f.w[ks], bx[ks], aw, 0, 0, 0); aa = __builtin_amdgcn_mfma_f32_16x16x32_bf16(f.a[ks], bx[2 + ks], aa, 0, 0, 0); }
; #pragma unroll
;             for (int ks = 0; ks < 4; ++ks) ag = __builtin_amdgcn_mfma_f32_16x16x32_bf16(f.gq[ks], bx[4 + ks], ag, 0, 0, 0);
;             const int c = nt * 16 + 4 * g;
;             f32x4 dec; float av[4];
; #pragma unroll
;             for (int e = 0; e < 4; ++e) {
;                 const float x = f.w0[e] + aw[e];
;                 const float sp = fmaxf(-x, 0.f) + log1pf(expf(-fabsf(x)));
;                 dec[e] = expf(-expf(-sp - 0.5f));
;                 av[e] = sigmoidf_(f.a0[e] + aa[e]);
;             }
;             *(f32x4*)(DEC + (size_t)row * 512 + c) = dec;
;             *(u32x2*)(AB + (size_t)row * 512 + c) = (u32x2){pk2(av[0], av[1]), pk2(av[2], av[3])};
;             *(u32x2*)(GG + (size_t)row * 512 + c) = (u32x2){pk2(ag[0], ag[1]), pk2(ag[2], ag[3])};
;         };
;         WF fa, fb;
;         ldw(fa, 0);
; #pragma unroll 1
;         for (int nt = 0; nt < 32; nt += 2) {
;             ldw(fb, nt + 1);
;             tile(fa, nt);
;             ldw(fa, (nt + 2) & 31);
;             tile(fb, nt + 1);
	ds_read_b128 v[16:19], v140 offset:0
	ds_read_b128 v[20:23], v140 offset:1024
	ds_read_b128 v[24:27], v140 offset:2048
	ds_read_b128 v[28:31], v140 offset:3072
	ds_read_b128 v[32:35], v140 offset:4096
	ds_read_b128 v[36:39], v140 offset:5120
	ds_read_b128 v[40:43], v140 offset:6144
	ds_read_b128 v[44:47], v140 offset:7168
	ds_read_b128 v[48:51], v134
	ds_read_b128 v[52:55], v134 offset:2048
	v_add_u32_e32 v134, 64, v134
	s_waitcnt vmcnt(0)
	ds_write_b128 v144, v[64:67] offset:16384
	ds_write_b128 v144, v[68:71] offset:17408
	global_load_dwordx4 v[56:59], v138, s[62:63]
	global_load_dwordx4 v[60:63], v139, s[62:63]
	s_add_u32 s62, s62, s64
	s_addc_u32 s63, s63, 0
	s_waitcnt lgkmcnt(0)
	v_mfma_f32_16x16x32_bf16 v[96:99], v[16:19], v[184:187], 0
	v_mfma_f32_16x16x32_bf16 v[100:103], v[24:27], v[192:195], 0
	v_mfma_f32_16x16x32_bf16 v[104:107], v[32:35], v[200:203], 0
	v_mfma_f32_16x16x32_bf16 v[96:99], v[20:23], v[188:191], v[96:99]
	v_mfma_f32_16x16x32_bf16 v[100:103], v[28:31], v[196:199], v[100:103]
	v_mfma_f32_16x16x32_bf16 v[104:107], v[36:39], v[204:207], v[104:107]
	v_mfma_f32_16x16x32_bf16 v[104:107], v[40:43], v[208:211], v[104:107]
	v_mfma_f32_16x16x32_bf16 v[104:107], v[44:47], v[212:215], v[104:107]
	s_nop 4
	v_add_f32_e32 v108, v48, v96
	v_add_f32_e32 v109, v49, v97
	v_add_f32_e32 v110, v50, v98
	v_add_f32_e32 v111, v51, v99
	v_add_f32_e32 v112, v52, v100
	v_add_f32_e32 v113, v53, v101
	v_add_f32_e32 v114, v54, v102
	v_add_f32_e32 v115, v55, v103
	v_mul_f32_e32 v108, 0xbfb8aa3b, v108
	v_mul_f32_e32 v109, 0xbfb8aa3b, v109
	v_mul_f32_e32 v110, 0xbfb8aa3b, v110
	v_mul_f32_e32 v111, 0xbfb8aa3b, v111
	v_mul_f32_e32 v112, 0xbfb8aa3b, v112
	v_mul_f32_e32 v113, 0xbfb8aa3b, v113
	v_mul_f32_e32 v114, 0xbfb8aa3b, v114
	v_mul_f32_e32 v115, 0xbfb8aa3b, v115
	v_exp_f32_e32 v108, v108
	v_exp_f32_e32 v109, v109
	v_exp_f32_e32 v110, v110
	v_exp_f32_e32 v111, v111
	v_exp_f32_e32 v112, v112
	v_exp_f32_e32 v113, v113
	v_exp_f32_e32 v114, v114
	v_exp_f32_e32 v115, v115
	v_add_f32_e32 v108, 1.0, v108
	v_add_f32_e32 v109, 1.0, v109
	v_add_f32_e32 v110, 1.0, v110
	v_add_f32_e32 v111, 1.0, v111
	v_add_f32_e32 v112, 1.0, v112
	v_add_f32_e32 v113, 1.0, v113
	v_add_f32_e32 v114, 1.0, v114
	v_add_f32_e32 v115, 1.0, v115
	v_rcp_f32_e32 v108, v108
	v_rcp_f32_e32 v109, v109
	v_rcp_f32_e32 v110, v110
	v_rcp_f32_e32 v111, v111
	v_rcp_f32_e32 v112, v112
	v_rcp_f32_e32 v113, v113
	v_rcp_f32_e32 v114, v114
	v_rcp_f32_e32 v115, v115
	v_mul_f32_e32 v108, 0xbf60028b, v108
	v_mul_f32_e32 v109, 0xbf60028b, v109
	v_mul_f32_e32 v110, 0xbf60028b, v110
	v_mul_f32_e32 v111, 0xbf60028b, v111
	v_cvt_pk_bf16_f32 v116, v112, v113
	v_cvt_pk_bf16_f32 v117, v114, v115
	v_exp_f32_e32 v108, v108
	v_exp_f32_e32 v109, v109
	v_exp_f32_e32 v110, v110
	v_exp_f32_e32 v111, v111
	v_cvt_pk_bf16_f32 v118, v104, v105
	v_cvt_pk_bf16_f32 v119, v106, v107
	global_store_dwordx2 v136, v[116:117], s[44:45]
	global_store_dwordx2 v136, v[118:119], s[46:47]
	global_store_dwordx4 v135, v[108:111], s[54:55]
	v_add_u32_e32 v136, 32, v136
	v_add_u32_e32 v135, 64, v135
	s_barrier
	s_mov_b32 s61, 6
.Llora_roll:
	ds_read_b128 v[16:19], v140 offset:16384
	ds_read_b128 v[20:23], v140 offset:17408
	ds_read_b128 v[24:27], v140 offset:18432
	ds_read_b128 v[28:31], v140 offset:19456
	ds_read_b128 v[32:35], v140 offset:20480
	ds_read_b128 v[36:39], v140 offset:21504
	ds_read_b128 v[40:43], v140 offset:22528
	ds_read_b128 v[44:47], v140 offset:23552
	ds_read_b128 v[88:91], v134
	ds_read_b128 v[92:95], v134 offset:2048
	v_add_u32_e32 v134, 64, v134
	s_waitcnt vmcnt(3)
	ds_write_b128 v144, v[56:59] offset:0
	ds_write_b128 v144, v[60:63] offset:1024
	global_load_dwordx4 v[64:67], v138, s[62:63]
	global_load_dwordx4 v[68:71], v139, s[62:63]
	s_add_u32 s62, s62, s64
	s_addc_u32 s63, s63, 0
	s_waitcnt lgkmcnt(0)
	v_mfma_f32_16x16x32_bf16 v[96:99], v[16:19], v[184:187], 0
	v_mfma_f32_16x16x32_bf16 v[100:103], v[24:27], v[192:195], 0
	v_mfma_f32_16x16x32_bf16 v[104:107], v[32:35], v[200:203], 0
	v_mfma_f32_16x16x32_bf16 v[96:99], v[20:23], v[188:191], v[96:99]
	v_mfma_f32_16x16x32_bf16 v[100:103], v[28:31], v[196:199], v[100:103]
	v_mfma_f32_16x16x32_bf16 v[104:107], v[36:39], v[204:207], v[104:107]
	v_mfma_f32_16x16x32_bf16 v[104:107], v[40:43], v[208:211], v[104:107]
	v_mfma_f32_16x16x32_bf16 v[104:107], v[44:47], v[212:215], v[104:107]
	s_nop 4
	v_add_f32_e32 v108, v88, v96
	v_add_f32_e32 v109, v89, v97
	v_add_f32_e32 v110, v90, v98
	v_add_f32_e32 v111, v91, v99
	v_add_f32_e32 v112, v92, v100
	v_add_f32_e32 v113, v93, v101
	v_add_f32_e32 v114, v94, v102
	v_add_f32_e32 v115, v95, v103
	v_mul_f32_e32 v108, 0xbfb8aa3b, v108
	v_mul_f32_e32 v109, 0xbfb8aa3b, v109
	v_mul_f32_e32 v110, 0xbfb8aa3b, v110
	v_mul_f32_e32 v111, 0xbfb8aa3b, v111
	v_mul_f32_e32 v112, 0xbfb8aa3b, v112
	v_mul_f32_e32 v113, 0xbfb8aa3b, v113
	v_mul_f32_e32 v114, 0xbfb8aa3b, v114
	v_mul_f32_e32 v115, 0xbfb8aa3b, v115
	v_exp_f32_e32 v108, v108
	v_exp_f32_e32 v109, v109
	v_exp_f32_e32 v110, v110
	v_exp_f32_e32 v111, v111
	v_exp_f32_e32 v112, v112
	v_exp_f32_e32 v113, v113
	v_exp_f32_e32 v114, v114
	v_exp_f32_e32 v115, v115
	v_add_f32_e32 v108, 1.0, v108
	v_add_f32_e32 v109, 1.0, v109
	v_add_f32_e32 v110, 1.0, v110
	v_add_f32_e32 v111, 1.0, v111
	v_add_f32_e32 v112, 1.0, v112
	v_add_f32_e32 v113, 1.0, v113
	v_add_f32_e32 v114, 1.0, v114
	v_add_f32_e32 v115, 1.0, v115
	v_rcp_f32_e32 v108, v108
	v_rcp_f32_e32 v109, v109
	v_rcp_f32_e32 v110, v110
	v_rcp_f32_e32 v111, v111
	v_rcp_f32_e32 v112, v112
	v_rcp_f32_e32 v113, v113
	v_rcp_f32_e32 v114, v114
	v_rcp_f32_e32 v115, v115
	v_mul_f32_e32 v108, 0xbf60028b, v108
	v_mul_f32_e32 v109, 0xbf60028b, v109
	v_mul_f32_e32 v110, 0xbf60028b, v110
	v_mul_f32_e32 v111, 0xbf60028b, v111
	v_cvt_pk_bf16_f32 v116, v112, v113
	v_cvt_pk_bf16_f32 v117, v114, v115
	v_exp_f32_e32 v108, v108
	v_exp_f32_e32 v109, v109
	v_exp_f32_e32 v110, v110
	v_exp_f32_e32 v111, v111
	v_cvt_pk_bf16_f32 v118, v104, v105
	v_cvt_pk_bf16_f32 v119, v106, v107
	global_store_dwordx2 v136, v[116:117], s[44:45]
	global_store_dwordx2 v136, v[118:119], s[46:47]
	global_store_dwordx4 v135, v[108:111], s[54:55]
	v_add_u32_e32 v136, 32, v136
	v_add_u32_e32 v135, 64, v135
	s_barrier
; __device__ __forceinline__ unsigned pk2(float lo, float hi) { f32x2 v = {lo, hi}; bf16x2_t b = __builtin_convertvector(v, bf16x2_t); return __builtin_bit_cast(unsigned, b); }
; __device__ __forceinline__ float sigmoidf_(float x) { return frcp(1.f + fexp2(-1.4426950408889634f * x)); }
;     __device__ __forceinline__ const float* in(int i) const { return (const float*)ptr(i); }
; __device__ __forceinline__ void phase_lora(const Ctx& p, LAS unsigned char* lds) {
;     ...
;         auto ldw = [&](WF& f, int nt) {
;             const int n = nt * 16 + q, c = nt * 16 + 4 * g;
; #pragma unroll
;             for (int ks = 0; ks < 2; ++ks) { f.w[ks] = *(const bf16x8*)(w2T + n * 64 + ks * 32 + 8 * g); f.a[ks] = *(const bf16x8*)(a2T + n * 64 + ks * 32 + 8 * g); }
; #pragma unroll
;             for (int ks = 0; ks < 4; ++ks) f.gq[ks] = *(const bf16x8*)(g2T + n * 128 + ks * 32 + 8 * g);
;             f.w0 = *(const f32x4*)(p.in(18) + c); f.a0 = *(const f32x4*)(p.in(20) + c);
;         };
;         auto tile = [&](const WF& f, int nt) {
;             f32x4 aw = (f32x4){0.f, 0.f, 0.f, 0.f}, aa = aw, ag = aw;
; #pragma unroll
;             for (int ks = 0; ks < 2; ++ks) { aw = __builtin_amdgcn_mfma_f32_16x16x32_bf16(f.w[ks], bx[ks], aw, 0, 0, 0); aa = __builtin_amdgcn_mfma_f32_16x16x32_bf16(f.a[ks], bx[2 + ks], aa, 0, 0, 0); }
; #pragma unroll
;             for (int ks = 0; ks < 4; ++ks) ag = __builtin_amdgcn_mfma_f32_16x16x32_bf16(f.gq[ks], bx[4 + ks], ag, 0, 0, 0);
;             const int c = nt * 16 + 4 * g;
;             f32x4 dec; float av[4];
; #pragma unroll
;             for (int e = 0; e < 4; ++e) {
;                 const float x = f.w0[e] + aw[e];
;                 const float sp = fmaxf(-x, 0.f) + log1pf(expf(-fabsf(x)));
;                 dec[e] = expf(-expf(-sp - 0.5f));
;                 av[e] = sigmoidf_(f.a0[e] + aa[e]);
;             }
;             *(f32x4*)(DEC + (size_t)row * 512 + c) = dec;
;             *(u32x2*)(AB + (size_t)row * 512 + c) = (u32x2){pk2(av[0], av[1]), pk2(av[2], av[3])};
;             *(u32x2*)(GG + (size_t)row * 512 + c) = (u32x2){pk2(ag[0], ag[1]), pk2(ag[2], ag[3])};
;         };
;         WF fa, fb;
;         ldw(fa, 0);
; #pragma unroll 1
;         for (int nt = 0; nt < 32; nt += 2) {
;             ldw(fb, nt + 1);
;             tile(fa, nt);
;             ldw(fa, (nt + 2) & 31);
;             tile(fb, nt + 1);
	ds_read_b128 v[16:19], v140 offset:0
	ds_read_b128 v[20:23], v140 offset:1024
	ds_read_b128 v[24:27], v140 offset:2048
	ds_read_b128 v[28:31], v140 offset:3072
	ds_read_b128 v[32:35], v140 offset:4096
	ds_read_b128 v[36:39], v140 offset:5120
	ds_read_b128 v[40:43], v140 offset:6144
	ds_read_b128 v[44:47], v140 offset:7168
	ds_read_b128 v[48:51], v134
	ds_read_b128 v[52:55], v134 offset:2048
	v_add_u32_e32 v134, 64, v134
	s_waitcnt vmcnt(3)
	ds_write_b128 v144, v[64:67] offset:16384
	ds_write_b128 v144, v[68:71] offset:17408
	global_load_dwordx4 v[56:59], v138, s[62:63]
	global_load_dwordx4 v[60:63], v139, s[62:63]
	s_add_u32 s62, s62, s64
	s_addc_u32 s63, s63, 0
	s_waitcnt lgkmcnt(0)
	v_mfma_f32_16x16x32_bf16 v[96:99], v[16:19], v[184:187], 0
	v_mfma_f32_16x16x32_bf16 v[100:103], v[24:27], v[192:195], 0
	v_mfma_f32_16x16x32_bf16 v[104:107], v[32:35], v[200:203], 0
	v_mfma_f32_16x16x32_bf16 v[96:99], v[20:23], v[188:191], v[96:99]
	v_mfma_f32_16x16x32_bf16 v[100:103], v[28:31], v[196:199], v[100:103]
	v_mfma_f32_16x16x32_bf16 v[104:107], v[36:39], v[204:207], v[104:107]
	v_mfma_f32_16x16x32_bf16 v[104:107], v[40:43], v[208:211], v[104:107]
	v_mfma_f32_16x16x32_bf16 v[104:107], v[44:47], v[212:215], v[104:107]
	s_nop 4
	v_add_f32_e32 v108, v48, v96
	v_add_f32_e32 v109, v49, v97
	v_add_f32_e32 v110, v50, v98
	v_add_f32_e32 v111, v51, v99
	v_add_f32_e32 v112, v52, v100
	v_add_f32_e32 v113, v53, v101
	v_add_f32_e32 v114, v54, v102
	v_add_f32_e32 v115, v55, v103
	v_mul_f32_e32 v108, 0xbfb8aa3b, v108
	v_mul_f32_e32 v109, 0xbfb8aa3b, v109
	v_mul_f32_e32 v110, 0xbfb8aa3b, v110
	v_mul_f32_e32 v111, 0xbfb8aa3b, v111
	v_mul_f32_e32 v112, 0xbfb8aa3b, v112
	v_mul_f32_e32 v113, 0xbfb8aa3b, v113
	v_mul_f32_e32 v114, 0xbfb8aa3b, v114
	v_mul_f32_e32 v115, 0xbfb8aa3b, v115
	v_exp_f32_e32 v108, v108
	v_exp_f32_e32 v109, v109
	v_exp_f32_e32 v110, v110
	v_exp_f32_e32 v111, v111
	v_exp_f32_e32 v112, v112
	v_exp_f32_e32 v113, v113
	v_exp_f32_e32 v114, v114
	v_exp_f32_e32 v115, v115
	v_add_f32_e32 v108, 1.0, v108
	v_add_f32_e32 v109, 1.0, v109
	v_add_f32_e32 v110, 1.0, v110
	v_add_f32_e32 v111, 1.0, v111
	v_add_f32_e32 v112, 1.0, v112
	v_add_f32_e32 v113, 1.0, v113
	v_add_f32_e32 v114, 1.0, v114
	v_add_f32_e32 v115, 1.0, v115
	v_rcp_f32_e32 v108, v108
	v_rcp_f32_e32 v109, v109
	v_rcp_f32_e32 v110, v110
	v_rcp_f32_e32 v111, v111
	v_rcp_f32_e32 v112, v112
	v_rcp_f32_e32 v113, v113
	v_rcp_f32_e32 v114, v114
	v_rcp_f32_e32 v115, v115
	v_mul_f32_e32 v108, 0xbf60028b, v108
	v_mul_f32_e32 v109, 0xbf60028b, v109
	v_mul_f32_e32 v110, 0xbf60028b, v110
	v_mul_f32_e32 v111, 0xbf60028b, v111
	v_cvt_pk_bf16_f32 v116, v112, v113
	v_cvt_pk_bf16_f32 v117, v114, v115
	v_exp_f32_e32 v108, v108
	v_exp_f32_e32 v109, v109
	v_exp_f32_e32 v110, v110
	v_exp_f32_e32 v111, v111
	v_cvt_pk_bf16_f32 v118, v104, v105
	v_cvt_pk_bf16_f32 v119, v106, v107
	global_store_dwordx2 v136, v[116:117], s[44:45]
	global_store_dwordx2 v136, v[118:119], s[46:47]
	global_store_dwordx4 v135, v[108:111], s[54:55]
	v_add_u32_e32 v136, 32, v136
	v_add_u32_e32 v135, 64, v135
	s_barrier
	s_sub_u32 s61, s61, 1
	s_cmp_lg_u32 s61, 0
	s_cbranch_scc1 .Llora_roll
	ds_read_b128 v[16:19], v140 offset:16384
	ds_read_b128 v[20:23], v140 offset:17408
	ds_read_b128 v[24:27], v140 offset:18432
	ds_read_b128 v[28:31], v140 offset:19456
	ds_read_b128 v[32:35], v140 offset:20480
	ds_read_b128 v[36:39], v140 offset:21504
	ds_read_b128 v[40:43], v140 offset:22528
	ds_read_b128 v[44:47], v140 offset:23552
	ds_read_b128 v[88:91], v134
	ds_read_b128 v[92:95], v134 offset:2048
	v_add_u32_e32 v134, 64, v134
	s_waitcnt vmcnt(3)
	ds_write_b128 v144, v[56:59] offset:0
	ds_write_b128 v144, v[60:63] offset:1024
	global_load_dwordx4 v[64:67], v138, s[62:63]
	global_load_dwordx4 v[68:71], v139, s[62:63]
	s_add_u32 s62, s62, s64
	s_addc_u32 s63, s63, 0
	s_waitcnt lgkmcnt(0)
	v_mfma_f32_16x16x32_bf16 v[96:99], v[16:19], v[184:187], 0
	v_mfma_f32_16x16x32_bf16 v[100:103], v[24:27], v[192:195], 0
	v_mfma_f32_16x16x32_bf16 v[104:107], v[32:35], v[200:203], 0
	v_mfma_f32_16x16x32_bf16 v[96:99], v[20:23], v[188:191], v[96:99]
	v_mfma_f32_16x16x32_bf16 v[100:103], v[28:31], v[196:199], v[100:103]
	v_mfma_f32_16x16x32_bf16 v[104:107], v[36:39], v[204:207], v[104:107]
	v_mfma_f32_16x16x32_bf16 v[104:107], v[40:43], v[208:211], v[104:107]
	v_mfma_f32_16x16x32_bf16 v[104:107], v[44:47], v[212:215], v[104:107]
	s_nop 4
	v_add_f32_e32 v108, v88, v96
	v_add_f32_e32 v109, v89, v97
	v_add_f32_e32 v110, v90, v98
	v_add_f32_e32 v111, v91, v99
	v_add_f32_e32 v112, v92, v100
	v_add_f32_e32 v113, v93, v101
	v_add_f32_e32 v114, v94, v102
	v_add_f32_e32 v115, v95, v103
	v_mul_f32_e32 v108, 0xbfb8aa3b, v108
	v_mul_f32_e32 v109, 0xbfb8aa3b, v109
	v_mul_f32_e32 v110, 0xbfb8aa3b, v110
	v_mul_f32_e32 v111, 0xbfb8aa3b, v111
	v_mul_f32_e32 v112, 0xbfb8aa3b, v112
	v_mul_f32_e32 v113, 0xbfb8aa3b, v113
	v_mul_f32_e32 v114, 0xbfb8aa3b, v114
	v_mul_f32_e32 v115, 0xbfb8aa3b, v115
	v_exp_f32_e32 v108, v108
	v_exp_f32_e32 v109, v109
	v_exp_f32_e32 v110, v110
	v_exp_f32_e32 v111, v111
	v_exp_f32_e32 v112, v112
	v_exp_f32_e32 v113, v113
	v_exp_f32_e32 v114, v114
	v_exp_f32_e32 v115, v115
	v_add_f32_e32 v108, 1.0, v108
	v_add_f32_e32 v109, 1.0, v109
	v_add_f32_e32 v110, 1.0, v110
	v_add_f32_e32 v111, 1.0, v111
	v_add_f32_e32 v112, 1.0, v112
	v_add_f32_e32 v113, 1.0, v113
	v_add_f32_e32 v114, 1.0, v114
	v_add_f32_e32 v115, 1.0, v115
	v_rcp_f32_e32 v108, v108
	v_rcp_f32_e32 v109, v109
	v_rcp_f32_e32 v110, v110
	v_rcp_f32_e32 v111, v111
	v_rcp_f32_e32 v112, v112
	v_rcp_f32_e32 v113, v113
	v_rcp_f32_e32 v114, v114
	v_rcp_f32_e32 v115, v115
	v_mul_f32_e32 v108, 0xbf60028b, v108
	v_mul_f32_e32 v109, 0xbf60028b, v109
	v_mul_f32_e32 v110, 0xbf60028b, v110
	v_mul_f32_e32 v111, 0xbf60028b, v111
	v_cvt_pk_bf16_f32 v116, v112, v113
	v_cvt_pk_bf16_f32 v117, v114, v115
	v_exp_f32_e32 v108, v108
	v_exp_f32_e32 v109, v109
	v_exp_f32_e32 v110, v110
	v_exp_f32_e32 v111, v111
	v_cvt_pk_bf16_f32 v118, v104, v105
	v_cvt_pk_bf16_f32 v119, v106, v107
	global_store_dwordx2 v136, v[116:117], s[44:45]
	global_store_dwordx2 v136, v[118:119], s[46:47]
	global_store_dwordx4 v135, v[108:111], s[54:55]
	v_add_u32_e32 v136, 32, v136
	v_add_u32_e32 v135, 64, v135
	s_barrier
; __device__ __forceinline__ unsigned pk2(float lo, float hi) { f32x2 v = {lo, hi}; bf16x2_t b = __builtin_convertvector(v, bf16x2_t); return __builtin_bit_cast(unsigned, b); }
; __device__ __forceinline__ float sigmoidf_(float x) { return frcp(1.f + fexp2(-1.4426950408889634f * x)); }
;     __device__ __forceinline__ const float* in(int i) const { return (const float*)ptr(i); }
; __device__ __forceinline__ void phase_lora(const Ctx& p, LAS unsigned char* lds) {
;     ...
;         auto ldw = [&](WF& f, int nt) {
;             const int n = nt * 16 + q, c = nt * 16 + 4 * g;
; #pragma unroll
;             for (int ks = 0; ks < 2; ++ks) { f.w[ks] = *(const bf16x8*)(w2T + n * 64 + ks * 32 + 8 * g); f.a[ks] = *(const bf16x8*)(a2T + n * 64 + ks * 32 + 8 * g); }
; #pragma unroll
;             for (int ks = 0; ks < 4; ++ks) f.gq[ks] = *(const bf16x8*)(g2T + n * 128 + ks * 32 + 8 * g);
;             f.w0 = *(const f32x4*)(p.in(18) + c); f.a0 = *(const f32x4*)(p.in(20) + c);
;         };
;         auto tile = [&](const WF& f, int nt) {
;             f32x4 aw = (f32x4){0.f, 0.f, 0.f, 0.f}, aa = aw, ag = aw;
; #pragma unroll
;             for (int ks = 0; ks < 2; ++ks) { aw = __builtin_amdgcn_mfma_f32_16x16x32_bf16(f.w[ks], bx[ks], aw, 0, 0, 0); aa = __builtin_amdgcn_mfma_f32_16x16x32_bf16(f.a[ks], bx[2 + ks], aa, 0, 0, 0); }
; #pragma unroll
;             for (int ks = 0; ks < 4; ++ks) ag = __builtin_amdgcn_mfma_f32_16x16x32_bf16(f.gq[ks], bx[4 + ks], ag, 0, 0, 0);
;             const int c = nt * 16 + 4 * g;
;             f32x4 dec; float av[4];
; #pragma unroll
;             for (int e = 0; e < 4; ++e) {
;                 const float x = f.w0[e] + aw[e];
;                 const float sp = fmaxf(-x, 0.f) + log1pf(expf(-fabsf(x)));
;                 dec[e] = expf(-expf(-sp - 0.5f));
;                 av[e] = sigmoidf_(f.a0[e] + aa[e]);
;             }
;             *(f32x4*)(DEC + (size_t)row * 512 + c) = dec;
;             *(u32x2*)(AB + (size_t)row * 512 + c) = (u32x2){pk2(av[0], av[1]), pk2(av[2], av[3])};
;             *(u32x2*)(GG + (size_t)row * 512 + c) = (u32x2){pk2(ag[0], ag[1]), pk2(ag[2], ag[3])};
;         };
;         WF fa, fb;
;         ldw(fa, 0);
; #pragma unroll 1
;         for (int nt = 0; nt < 32; nt += 2) {
;             ldw(fb, nt + 1);
;             tile(fa, nt);
;             ldw(fa, (nt + 2) & 31);
;             tile(fb, nt + 1);
;         }
	ds_read_b128 v[16:19], v140 offset:0
	ds_read_b128 v[20:23], v140 offset:1024
	ds_read_b128 v[24:27], v140 offset:2048
	ds_read_b128 v[28:31], v140 offset:3072
	ds_read_b128 v[32:35], v140 offset:4096
	ds_read_b128 v[36:39], v140 offset:5120
	ds_read_b128 v[40:43], v140 offset:6144
	ds_read_b128 v[44:47], v140 offset:7168
	ds_read_b128 v[48:51], v134
	ds_read_b128 v[52:55], v134 offset:2048
	v_add_u32_e32 v134, 64, v134
	s_waitcnt vmcnt(3)
	ds_write_b128 v144, v[64:67] offset:16384
	ds_write_b128 v144, v[68:71] offset:17408
	s_waitcnt lgkmcnt(0)
	v_mfma_f32_16x16x32_bf16 v[96:99], v[16:19], v[184:187], 0
	v_mfma_f32_16x16x32_bf16 v[100:103], v[24:27], v[192:195], 0
	v_mfma_f32_16x16x32_bf16 v[104:107], v[32:35], v[200:203], 0
	v_mfma_f32_16x16x32_bf16 v[96:99], v[20:23], v[188:191], v[96:99]
	v_mfma_f32_16x16x32_bf16 v[100:103], v[28:31], v[196:199], v[100:103]
	v_mfma_f32_16x16x32_bf16 v[104:107], v[36:39], v[204:207], v[104:107]
	v_mfma_f32_16x16x32_bf16 v[104:107], v[40:43], v[208:211], v[104:107]
	v_mfma_f32_16x16x32_bf16 v[104:107], v[44:47], v[212:215], v[104:107]
	s_nop 4
	v_add_f32_e32 v108, v48, v96
	v_add_f32_e32 v109, v49, v97
	v_add_f32_e32 v110, v50, v98
	v_add_f32_e32 v111, v51, v99
	v_add_f32_e32 v112, v52, v100
	v_add_f32_e32 v113, v53, v101
	v_add_f32_e32 v114, v54, v102
	v_add_f32_e32 v115, v55, v103
	v_mul_f32_e32 v108, 0xbfb8aa3b, v108
	v_mul_f32_e32 v109, 0xbfb8aa3b, v109
	v_mul_f32_e32 v110, 0xbfb8aa3b, v110
	v_mul_f32_e32 v111, 0xbfb8aa3b, v111
	v_mul_f32_e32 v112, 0xbfb8aa3b, v112
	v_mul_f32_e32 v113, 0xbfb8aa3b, v113
	v_mul_f32_e32 v114, 0xbfb8aa3b, v114
	v_mul_f32_e32 v115, 0xbfb8aa3b, v115
	v_exp_f32_e32 v108, v108
	v_exp_f32_e32 v109, v109
	v_exp_f32_e32 v110, v110
	v_exp_f32_e32 v111, v111
	v_exp_f32_e32 v112, v112
	v_exp_f32_e32 v113, v113
	v_exp_f32_e32 v114, v114
	v_exp_f32_e32 v115, v115
	v_add_f32_e32 v108, 1.0, v108
	v_add_f32_e32 v109, 1.0, v109
	v_add_f32_e32 v110, 1.0, v110
	v_add_f32_e32 v111, 1.0, v111
	v_add_f32_e32 v112, 1.0, v112
	v_add_f32_e32 v113, 1.0, v113
	v_add_f32_e32 v114, 1.0, v114
	v_add_f32_e32 v115, 1.0, v115
	v_rcp_f32_e32 v108, v108
	v_rcp_f32_e32 v109, v109
	v_rcp_f32_e32 v110, v110
	v_rcp_f32_e32 v111, v111
	v_rcp_f32_e32 v112, v112
	v_rcp_f32_e32 v113, v113
	v_rcp_f32_e32 v114, v114
	v_rcp_f32_e32 v115, v115
	v_mul_f32_e32 v108, 0xbf60028b, v108
	v_mul_f32_e32 v109, 0xbf60028b, v109
	v_mul_f32_e32 v110, 0xbf60028b, v110
	v_mul_f32_e32 v111, 0xbf60028b, v111
	v_cvt_pk_bf16_f32 v116, v112, v113
	v_cvt_pk_bf16_f32 v117, v114, v115
	v_exp_f32_e32 v108, v108
	v_exp_f32_e32 v109, v109
	v_exp_f32_e32 v110, v110
	v_exp_f32_e32 v111, v111
	v_cvt_pk_bf16_f32 v118, v104, v105
	v_cvt_pk_bf16_f32 v119, v106, v107
	global_store_dwordx2 v136, v[116:117], s[44:45]
	global_store_dwordx2 v136, v[118:119], s[46:47]
	global_store_dwordx4 v135, v[108:111], s[54:55]
	v_add_u32_e32 v136, 32, v136
	v_add_u32_e32 v135, 64, v135
	s_barrier
	ds_read_b128 v[16:19], v140 offset:16384
	ds_read_b128 v[20:23], v140 offset:17408
	ds_read_b128 v[24:27], v140 offset:18432
	ds_read_b128 v[28:31], v140 offset:19456
	ds_read_b128 v[32:35], v140 offset:20480
	ds_read_b128 v[36:39], v140 offset:21504
	ds_read_b128 v[40:43], v140 offset:22528
	ds_read_b128 v[44:47], v140 offset:23552
	ds_read_b128 v[88:91], v134
	ds_read_b128 v[92:95], v134 offset:2048
	v_add_u32_e32 v134, 64, v134
	s_waitcnt lgkmcnt(0)
	v_mfma_f32_16x16x32_bf16 v[96:99], v[16:19], v[184:187], 0
	v_mfma_f32_16x16x32_bf16 v[100:103], v[24:27], v[192:195], 0
	v_mfma_f32_16x16x32_bf16 v[104:107], v[32:35], v[200:203], 0
	v_mfma_f32_16x16x32_bf16 v[96:99], v[20:23], v[188:191], v[96:99]
	v_mfma_f32_16x16x32_bf16 v[100:103], v[28:31], v[196:199], v[100:103]
	v_mfma_f32_16x16x32_bf16 v[104:107], v[36:39], v[204:207], v[104:107]
	v_mfma_f32_16x16x32_bf16 v[104:107], v[40:43], v[208:211], v[104:107]
	v_mfma_f32_16x16x32_bf16 v[104:107], v[44:47], v[212:215], v[104:107]
	s_nop 4
	v_add_f32_e32 v108, v88, v96
	v_add_f32_e32 v109, v89, v97
	v_add_f32_e32 v110, v90, v98
	v_add_f32_e32 v111, v91, v99
	v_add_f32_e32 v112, v92, v100
	v_add_f32_e32 v113, v93, v101
	v_add_f32_e32 v114, v94, v102
	v_add_f32_e32 v115, v95, v103
	v_mul_f32_e32 v108, 0xbfb8aa3b, v108
	v_mul_f32_e32 v109, 0xbfb8aa3b, v109
	v_mul_f32_e32 v110, 0xbfb8aa3b, v110
	v_mul_f32_e32 v111, 0xbfb8aa3b, v111
	v_mul_f32_e32 v112, 0xbfb8aa3b, v112
	v_mul_f32_e32 v113, 0xbfb8aa3b, v113
	v_mul_f32_e32 v114, 0xbfb8aa3b, v114
	v_mul_f32_e32 v115, 0xbfb8aa3b, v115
	v_exp_f32_e32 v108, v108
	v_exp_f32_e32 v109, v109
	v_exp_f32_e32 v110, v110
	v_exp_f32_e32 v111, v111
	v_exp_f32_e32 v112, v112
	v_exp_f32_e32 v113, v113
	v_exp_f32_e32 v114, v114
	v_exp_f32_e32 v115, v115
	v_add_f32_e32 v108, 1.0, v108
	v_add_f32_e32 v109, 1.0, v109
	v_add_f32_e32 v110, 1.0, v110
	v_add_f32_e32 v111, 1.0, v111
	v_add_f32_e32 v112, 1.0, v112
	v_add_f32_e32 v113, 1.0, v113
	v_add_f32_e32 v114, 1.0, v114
	v_add_f32_e32 v115, 1.0, v115
	v_rcp_f32_e32 v108, v108
	v_rcp_f32_e32 v109, v109
	v_rcp_f32_e32 v110, v110
	v_rcp_f32_e32 v111, v111
	v_rcp_f32_e32 v112, v112
	v_rcp_f32_e32 v113, v113
	v_rcp_f32_e32 v114, v114
	v_rcp_f32_e32 v115, v115
	v_mul_f32_e32 v108, 0xbf60028b, v108
	v_mul_f32_e32 v109, 0xbf60028b, v109
	v_mul_f32_e32 v110, 0xbf60028b, v110
	v_mul_f32_e32 v111, 0xbf60028b, v111
	v_cvt_pk_bf16_f32 v116, v112, v113
	v_cvt_pk_bf16_f32 v117, v114, v115
	v_exp_f32_e32 v108, v108
	v_exp_f32_e32 v109, v109
	v_exp_f32_e32 v110, v110
	v_exp_f32_e32 v111, v111
	v_cvt_pk_bf16_f32 v118, v104, v105
	v_cvt_pk_bf16_f32 v119, v106, v107
	global_store_dwordx2 v136, v[116:117], s[44:45]
	global_store_dwordx2 v136, v[118:119], s[46:47]
	global_store_dwordx4 v135, v[108:111], s[54:55]
	v_add_u32_e32 v136, 32, v136
	v_add_u32_e32 v135, 64, v135
	s_cmp_lt_u32 s28, 32
	s_cbranch_scc0 .Llora_done
	s_mov_b32 s57, 1
	s_lshr_b32 s2, s28, 2
	s_add_i32 s26, s2, 0x400
	s_branch .Llora_item
